# k0,k1 MFMAs of each accumulator issued back-to-back (SrcC forwarding) in clean blocks
# speedup vs baseline: 1.0114x; 1.0067x over previous
; #define PG8_STAGE(bufoff, gbase, voff) do { _Pragma("unroll") for (int _i = 0; _i < 2; ++_i) \
;         __builtin_amdgcn_global_load_lds((const unsigned*)((const char*)(gbase) + (voff)[_i]), (PG8_LAS unsigned*)(lds + (bufoff) + ldsw + _i * 8192), 16, 0, 0); } while (0)
; #define PG8_LDA(dst, b, h) do { _Pragma("unroll") for (int m = 0; m < 4; ++m) _Pragma("unroll") for (int k = 0; k < 2; ++k) dst[m][k] = *(const PG8_LAS bf16x8*)(lds + PG8_SA(b, h) + aoff + m * 2048 + k * 1024); } while (0)
; #define PG8_LDB(dst, b, h) do { _Pragma("unroll") for (int n = 0; n < 2; ++n) _Pragma("unroll") for (int k = 0; k < 2; ++k) dst[n][k] = *(const PG8_LAS bf16x8*)(lds + PG8_SB(b, h) + boff + n * 2048 + k * 1024); } while (0)
; #define PG8_MMA(ai, bj, At, Bt) do { __builtin_amdgcn_s_setprio(1); _Pragma("unroll") for (int m = 0; m < 4; ++m) _Pragma("unroll") for (int n = 0; n < 2; ++n) _Pragma("unroll") for (int k = 0; k < 2; ++k) \
;         acc[ai][bj][m][n] = __builtin_amdgcn_mfma_f32_16x16x32_bf16(Bt[n][k], At[m][k], acc[ai][bj][m][n], 0, 0, 0); __builtin_amdgcn_s_setprio(0); } while (0)
; #define PG8_WAIT_V(n) asm volatile("s_waitcnt vmcnt(" #n ")" ::: "memory")
; #define PG8_WAIT_L(n) asm volatile("s_waitcnt lgkmcnt(" #n ")" ::: "memory")
; template <class Epi, class Sched, bool ALIGN_EPI = true>
; __device__ __forceinline__ void gemm_phase(PG8_LAS unsigned char* lds, const Gemm g, const Sched& S, const Epi& E, const int tid) {
;     ...
;         for (int t = 0; t < nt; t += 2) {
;             const bool last = (t == nt - 2);
;             const char* a1 = cA + (size_t)(t + 1) * kstep;
;             const char* a2 = last ? nA : cA + (size_t)(t + 2) * kstep; const char* b2 = last ? nB : cB + (size_t)(t + 2) * kstep;
;             const char* a3 = a2 + kstep; const char* b3 = b2 + kstep;
;             if (last && has_next) S.a_ready(nxt);
;             PG8_LDB(B0, 0, 0); PG8_LDB(B1, 0, 1); PG8_SCHED; PG8_LDA(At, 0, 0); PG8_STAGE(PG8_SA(1, 1), a1 + hstepA, voffA);
;             PG8_WAIT_V(8); PG8_WAIT_L(0); PG8_BAR; PG8_MMA(0, 0, At, B0); PG8_MMA(0, 1, At, B1); PG8_BAR; PG8_SCHED;
;             PG8_LDA(At, 0, 1); PG8_STAGE(PG8_SB(0, 0), b2, voffB); PG8_STAGE(PG8_SB(0, 1), b2 + hstepB, voffB); PG8_STAGE(PG8_SA(0, 0), a2, voffA);
;             PG8_WAIT_V(8); PG8_WAIT_L(0); PG8_BAR; PG8_MMA(1, 0, At, B0); PG8_MMA(1, 1, At, B1); PG8_BAR; PG8_SCHED;
.LBB0_426:
	s_add_u32 s15, s12, 0xfff80080
	s_addc_u32 s16, s13, -1
	s_add_i32 s17, 0, 0x10000
	s_cmp_eq_u32 s53, 4
	s_cselect_b32 s63, s1, s16
	s_cselect_b32 s62, s5, s15
	s_cselect_b32 s23, s8, s21
	s_cselect_b32 s22, s9, s20
	s_add_i32 s15, 0, 0x14000
	v_add_u32_e32 v72, s17, v251
	v_add_u32_e32 v136, s15, v251
	ds_read_b128 v[60:63], v72
	ds_read_b128 v[64:67], v72 offset:1024
	ds_read_b128 v[68:71], v72 offset:2048
	ds_read_b128 v[72:75], v72 offset:3072
	ds_read_b128 v[100:103], v136
	ds_read_b128 v[112:115], v136 offset:1024
	ds_read_b128 v[116:119], v136 offset:2048
	ds_read_b128 v[136:139], v136 offset:3072
	v_lshl_add_u64 v[196:197], s[12:13], 0, v[216:217]
	s_add_i32 m0, s11, 0xc000
	ds_read_b128 v[140:143], v252
	ds_read_b128 v[152:155], v252 offset:1024
	ds_read_b128 v[156:159], v252 offset:2048
	ds_read_b128 v[168:171], v252 offset:3072
	ds_read_b128 v[172:175], v252 offset:4096
	ds_read_b128 v[184:187], v252 offset:5120
	ds_read_b128 v[188:191], v252 offset:6144
	ds_read_b128 v[192:195], v252 offset:7168
	global_load_lds_dwordx4 v[196:197], off
	v_lshl_add_u64 v[196:197], s[12:13], 0, v[218:219]
	s_add_i32 m0, s11, 0xe000
	s_nop 0
	global_load_lds_dwordx4 v[196:197], off
	s_waitcnt vmcnt(8)
	s_waitcnt lgkmcnt(0)
	s_barrier
	s_waitcnt lgkmcnt(0)
	v_mfma_f32_16x16x32_bf16 v[180:183], v[60:63], v[140:143], v[180:183]
	v_mfma_f32_16x16x32_bf16 v[180:183], v[64:67], v[152:155], v[180:183]
	v_mfma_f32_16x16x32_bf16 v[176:179], v[68:71], v[140:143], v[176:179]
	v_mfma_f32_16x16x32_bf16 v[176:179], v[72:75], v[152:155], v[176:179]
	v_mfma_f32_16x16x32_bf16 v[148:151], v[60:63], v[156:159], v[148:151]
	v_mfma_f32_16x16x32_bf16 v[148:151], v[64:67], v[168:171], v[148:151]
	v_mfma_f32_16x16x32_bf16 v[144:147], v[68:71], v[156:159], v[144:147]
	v_mfma_f32_16x16x32_bf16 v[144:147], v[72:75], v[168:171], v[144:147]
	v_mfma_f32_16x16x32_bf16 v[124:127], v[60:63], v[172:175], v[124:127]
	v_mfma_f32_16x16x32_bf16 v[124:127], v[64:67], v[184:187], v[124:127]
	v_mfma_f32_16x16x32_bf16 v[120:123], v[68:71], v[172:175], v[120:123]
	v_mfma_f32_16x16x32_bf16 v[120:123], v[72:75], v[184:187], v[120:123]
	v_mfma_f32_16x16x32_bf16 v[96:99], v[60:63], v[188:191], v[96:99]
	v_mfma_f32_16x16x32_bf16 v[96:99], v[64:67], v[192:195], v[96:99]
	v_mfma_f32_16x16x32_bf16 v[92:95], v[68:71], v[188:191], v[92:95]
	v_mfma_f32_16x16x32_bf16 v[92:95], v[72:75], v[192:195], v[92:95]
	v_mfma_f32_16x16x32_bf16 v[164:167], v[100:103], v[140:143], v[164:167]
	v_mfma_f32_16x16x32_bf16 v[132:135], v[100:103], v[156:159], v[132:135]
	v_mfma_f32_16x16x32_bf16 v[128:131], v[116:119], v[156:159], v[128:131]
	v_mfma_f32_16x16x32_bf16 v[108:111], v[100:103], v[172:175], v[108:111]
	v_mfma_f32_16x16x32_bf16 v[104:107], v[116:119], v[172:175], v[104:107]
	v_mfma_f32_16x16x32_bf16 v[88:91], v[100:103], v[188:191], v[88:91]
	v_mfma_f32_16x16x32_bf16 v[84:87], v[116:119], v[188:191], v[84:87]
	v_mfma_f32_16x16x32_bf16 v[164:167], v[112:115], v[152:155], v[164:167]
	v_mfma_f32_16x16x32_bf16 v[140:143], v[116:119], v[140:143], v[160:163]
	v_mfma_f32_16x16x32_bf16 v[132:135], v[112:115], v[168:171], v[132:135]
	v_mfma_f32_16x16x32_bf16 v[128:131], v[136:139], v[168:171], v[128:131]
	v_mfma_f32_16x16x32_bf16 v[108:111], v[112:115], v[184:187], v[108:111]
	v_mfma_f32_16x16x32_bf16 v[104:107], v[136:139], v[184:187], v[104:107]
	v_mfma_f32_16x16x32_bf16 v[88:91], v[112:115], v[192:195], v[88:91]
	v_mfma_f32_16x16x32_bf16 v[84:87], v[136:139], v[192:195], v[84:87]
	v_mfma_f32_16x16x32_bf16 v[140:143], v[136:139], v[152:155], v[140:143]
	s_barrier
	s_add_i32 s16, s17, s67
	v_lshl_add_u64 v[200:201], s[22:23], 0, v[2:3]
	s_mov_b32 m0, s16
	ds_read_b128 v[152:155], v252 offset:16384
	ds_read_b128 v[156:159], v252 offset:17408
	ds_read_b128 v[160:163], v252 offset:18432
	ds_read_b128 v[168:171], v252 offset:19456
	ds_read_b128 v[172:175], v252 offset:20480
	ds_read_b128 v[184:187], v252 offset:21504
	ds_read_b128 v[188:191], v252 offset:22528
	ds_read_b128 v[192:195], v252 offset:23552
	global_load_lds_dwordx4 v[200:201], off
	s_add_i32 m0, s16, 0x2000
	s_add_u32 s78, s22, 0x20000
	v_lshl_add_u64 v[202:203], s[22:23], 0, v[210:211]
	s_addc_u32 s79, s23, 0
	s_add_i32 s15, s15, s67
	global_load_lds_dwordx4 v[202:203], off
	v_lshl_add_u64 v[196:197], s[78:79], 0, v[2:3]
	s_mov_b32 m0, s15
	v_lshl_add_u64 v[204:205], s[62:63], 0, v[214:215]
	global_load_lds_dwordx4 v[196:197], off
	v_lshl_add_u64 v[196:197], s[78:79], 0, v[210:211]
	s_add_i32 m0, s15, 0x2000
	v_lshl_add_u64 v[206:207], s[62:63], 0, v[212:213]
	global_load_lds_dwordx4 v[196:197], off
	s_mov_b32 m0, s11
	s_nop 0
	global_load_lds_dwordx4 v[204:205], off
	s_mov_b32 m0, s68
	s_nop 0
	global_load_lds_dwordx4 v[206:207], off
	s_waitcnt vmcnt(8)
	s_waitcnt lgkmcnt(0)
	s_barrier
; #define PG8_STAGE(bufoff, gbase, voff) do { _Pragma("unroll") for (int _i = 0; _i < 2; ++_i) \
;         __builtin_amdgcn_global_load_lds((const unsigned*)((const char*)(gbase) + (voff)[_i]), (PG8_LAS unsigned*)(lds + (bufoff) + ldsw + _i * 8192), 16, 0, 0); } while (0)
; #define PG8_LDA(dst, b, h) do { _Pragma("unroll") for (int m = 0; m < 4; ++m) _Pragma("unroll") for (int k = 0; k < 2; ++k) dst[m][k] = *(const PG8_LAS bf16x8*)(lds + PG8_SA(b, h) + aoff + m * 2048 + k * 1024); } while (0)
; #define PG8_LDB(dst, b, h) do { _Pragma("unroll") for (int n = 0; n < 2; ++n) _Pragma("unroll") for (int k = 0; k < 2; ++k) dst[n][k] = *(const PG8_LAS bf16x8*)(lds + PG8_SB(b, h) + boff + n * 2048 + k * 1024); } while (0)
; #define PG8_MMA(ai, bj, At, Bt) do { __builtin_amdgcn_s_setprio(1); _Pragma("unroll") for (int m = 0; m < 4; ++m) _Pragma("unroll") for (int n = 0; n < 2; ++n) _Pragma("unroll") for (int k = 0; k < 2; ++k) \
;         acc[ai][bj][m][n] = __builtin_amdgcn_mfma_f32_16x16x32_bf16(Bt[n][k], At[m][k], acc[ai][bj][m][n], 0, 0, 0); __builtin_amdgcn_s_setprio(0); } while (0)
; #define PG8_WAIT_V(n) asm volatile("s_waitcnt vmcnt(" #n ")" ::: "memory")
; #define PG8_WAIT_L(n) asm volatile("s_waitcnt lgkmcnt(" #n ")" ::: "memory")
; #define PG8_BAR __builtin_amdgcn_s_barrier()
; #define PG8_SCHED __builtin_amdgcn_sched_barrier(0)
; template <class Epi, class Sched, bool ALIGN_EPI = true>
; __device__ __forceinline__ void gemm_phase(PG8_LAS unsigned char* lds, const Gemm g, const Sched& S, const Epi& E, const int tid) {
;     ...
;             PG8_WAIT_V(8); PG8_WAIT_L(0); PG8_BAR; PG8_MMA(1, 0, At, B0); PG8_MMA(1, 1, At, B1); PG8_BAR; PG8_SCHED;
;             PG8_LDB(B0, 1, 0); PG8_LDB(B1, 1, 1); PG8_SCHED; PG8_LDA(At, 1, 0); PG8_STAGE(PG8_SA(0, 1), a2 + hstepA, voffA);
;             PG8_WAIT_V(8); PG8_WAIT_L(0); PG8_BAR; PG8_MMA(0, 0, At, B0); PG8_MMA(0, 1, At, B1); PG8_BAR; PG8_SCHED;
	s_waitcnt lgkmcnt(0)
	v_mfma_f32_16x16x32_bf16 v[80:83], v[60:63], v[152:155], v[80:83]
	v_mfma_f32_16x16x32_bf16 v[80:83], v[64:67], v[156:159], v[80:83]
	v_mfma_f32_16x16x32_bf16 v[76:79], v[68:71], v[152:155], v[76:79]
	v_mfma_f32_16x16x32_bf16 v[76:79], v[72:75], v[156:159], v[76:79]
	v_mfma_f32_16x16x32_bf16 v[48:51], v[60:63], v[160:163], v[48:51]
	v_mfma_f32_16x16x32_bf16 v[48:51], v[64:67], v[168:171], v[48:51]
	v_mfma_f32_16x16x32_bf16 v[44:47], v[68:71], v[160:163], v[44:47]
	v_mfma_f32_16x16x32_bf16 v[44:47], v[72:75], v[168:171], v[44:47]
	v_mfma_f32_16x16x32_bf16 v[32:35], v[60:63], v[172:175], v[32:35]
	v_mfma_f32_16x16x32_bf16 v[32:35], v[64:67], v[184:187], v[32:35]
	v_mfma_f32_16x16x32_bf16 v[28:31], v[68:71], v[172:175], v[28:31]
	v_mfma_f32_16x16x32_bf16 v[28:31], v[72:75], v[184:187], v[28:31]
	v_mfma_f32_16x16x32_bf16 v[16:19], v[60:63], v[188:191], v[16:19]
	v_mfma_f32_16x16x32_bf16 v[16:19], v[64:67], v[192:195], v[16:19]
	v_mfma_f32_16x16x32_bf16 v[12:15], v[68:71], v[188:191], v[12:15]
	v_mfma_f32_16x16x32_bf16 v[12:15], v[72:75], v[192:195], v[12:15]
	v_mfma_f32_16x16x32_bf16 v[56:59], v[100:103], v[152:155], v[56:59]
	v_mfma_f32_16x16x32_bf16 v[56:59], v[112:115], v[156:159], v[56:59]
	v_mfma_f32_16x16x32_bf16 v[52:55], v[116:119], v[152:155], v[52:55]
	v_mfma_f32_16x16x32_bf16 v[52:55], v[136:139], v[156:159], v[52:55]
	v_mfma_f32_16x16x32_bf16 v[40:43], v[100:103], v[160:163], v[40:43]
	v_mfma_f32_16x16x32_bf16 v[40:43], v[112:115], v[168:171], v[40:43]
	v_mfma_f32_16x16x32_bf16 v[36:39], v[116:119], v[160:163], v[36:39]
	v_mfma_f32_16x16x32_bf16 v[36:39], v[136:139], v[168:171], v[36:39]
	v_mfma_f32_16x16x32_bf16 v[24:27], v[100:103], v[172:175], v[24:27]
	v_mfma_f32_16x16x32_bf16 v[24:27], v[112:115], v[184:187], v[24:27]
	v_mfma_f32_16x16x32_bf16 v[20:23], v[116:119], v[172:175], v[20:23]
	v_mfma_f32_16x16x32_bf16 v[20:23], v[136:139], v[184:187], v[20:23]
	v_mfma_f32_16x16x32_bf16 v[8:11], v[100:103], v[188:191], v[8:11]
	v_mfma_f32_16x16x32_bf16 v[8:11], v[112:115], v[192:195], v[8:11]
	v_mfma_f32_16x16x32_bf16 v[4:7], v[116:119], v[188:191], v[4:7]
	v_mfma_f32_16x16x32_bf16 v[4:7], v[136:139], v[192:195], v[4:7]
	s_barrier
	s_add_i32 s15, 0, 0x18000
	s_add_i32 s16, 0, 0x1c000
	v_add_u32_e32 v72, s15, v251
	v_add_u32_e32 v136, s16, v251
	ds_read_b128 v[60:63], v72
	ds_read_b128 v[64:67], v72 offset:1024
	ds_read_b128 v[68:71], v72 offset:2048
	ds_read_b128 v[72:75], v72 offset:3072
	ds_read_b128 v[100:103], v136
	ds_read_b128 v[112:115], v136 offset:1024
	ds_read_b128 v[116:119], v136 offset:2048
	ds_read_b128 v[136:139], v136 offset:3072
	s_add_u32 s62, s62, 0x80000
	s_addc_u32 s63, s63, 0
	s_mov_b32 m0, s69
	v_lshl_add_u64 v[160:161], s[62:63], 0, v[214:215]
	ds_read_b128 v[152:155], v252 offset:32768
	ds_read_b128 v[156:159], v252 offset:33792
	ds_read_b128 v[168:171], v252 offset:34816
	ds_read_b128 v[172:175], v252 offset:35840
	ds_read_b128 v[184:187], v252 offset:36864
	ds_read_b128 v[188:191], v252 offset:37888
	ds_read_b128 v[192:195], v252 offset:38912
	ds_read_b128 v[196:199], v252 offset:39936
	global_load_lds_dwordx4 v[160:161], off
	v_lshl_add_u64 v[160:161], s[62:63], 0, v[212:213]
	s_mov_b32 m0, s70
	s_nop 0
	global_load_lds_dwordx4 v[160:161], off
	s_waitcnt vmcnt(8)
	s_waitcnt lgkmcnt(0)
	s_barrier
	s_waitcnt lgkmcnt(0)
	v_mfma_f32_16x16x32_bf16 v[160:163], v[60:63], v[152:155], v[180:183]
	v_mfma_f32_16x16x32_bf16 v[180:183], v[64:67], v[156:159], v[160:163]
	v_mfma_f32_16x16x32_bf16 v[160:163], v[68:71], v[152:155], v[176:179]
	v_mfma_f32_16x16x32_bf16 v[148:151], v[60:63], v[168:171], v[148:151]
	v_mfma_f32_16x16x32_bf16 v[144:147], v[68:71], v[168:171], v[144:147]
	v_mfma_f32_16x16x32_bf16 v[124:127], v[60:63], v[184:187], v[124:127]
	v_mfma_f32_16x16x32_bf16 v[120:123], v[68:71], v[184:187], v[120:123]
	v_mfma_f32_16x16x32_bf16 v[96:99], v[60:63], v[192:195], v[96:99]
	v_mfma_f32_16x16x32_bf16 v[92:95], v[68:71], v[192:195], v[92:95]
	v_mfma_f32_16x16x32_bf16 v[176:179], v[72:75], v[156:159], v[160:163]
	v_mfma_f32_16x16x32_bf16 v[148:151], v[64:67], v[172:175], v[148:151]
	v_mfma_f32_16x16x32_bf16 v[144:147], v[72:75], v[172:175], v[144:147]
	v_mfma_f32_16x16x32_bf16 v[124:127], v[64:67], v[188:191], v[124:127]
	v_mfma_f32_16x16x32_bf16 v[120:123], v[72:75], v[188:191], v[120:123]
	v_mfma_f32_16x16x32_bf16 v[96:99], v[64:67], v[196:199], v[96:99]
	v_mfma_f32_16x16x32_bf16 v[92:95], v[72:75], v[196:199], v[92:95]
	v_mfma_f32_16x16x32_bf16 v[160:163], v[100:103], v[152:155], v[164:167]
	v_mfma_f32_16x16x32_bf16 v[140:143], v[116:119], v[152:155], v[140:143]
	v_mfma_f32_16x16x32_bf16 v[132:135], v[100:103], v[168:171], v[132:135]
	v_mfma_f32_16x16x32_bf16 v[128:131], v[116:119], v[168:171], v[128:131]
	v_mfma_f32_16x16x32_bf16 v[108:111], v[100:103], v[184:187], v[108:111]
	v_mfma_f32_16x16x32_bf16 v[104:107], v[116:119], v[184:187], v[104:107]
	v_mfma_f32_16x16x32_bf16 v[88:91], v[100:103], v[192:195], v[88:91]
	v_mfma_f32_16x16x32_bf16 v[84:87], v[116:119], v[192:195], v[84:87]
	v_mfma_f32_16x16x32_bf16 v[164:167], v[112:115], v[156:159], v[160:163]
	v_mfma_f32_16x16x32_bf16 v[160:163], v[136:139], v[156:159], v[140:143]
	v_mfma_f32_16x16x32_bf16 v[132:135], v[112:115], v[172:175], v[132:135]
	v_mfma_f32_16x16x32_bf16 v[128:131], v[136:139], v[172:175], v[128:131]
	v_mfma_f32_16x16x32_bf16 v[108:111], v[112:115], v[188:191], v[108:111]
	v_mfma_f32_16x16x32_bf16 v[104:107], v[136:139], v[188:191], v[104:107]
	v_mfma_f32_16x16x32_bf16 v[88:91], v[112:115], v[196:199], v[88:91]
	v_mfma_f32_16x16x32_bf16 v[84:87], v[136:139], v[196:199], v[84:87]
	s_barrier
; #define PG8_STAGE(bufoff, gbase, voff) do { _Pragma("unroll") for (int _i = 0; _i < 2; ++_i) \
;         __builtin_amdgcn_global_load_lds((const unsigned*)((const char*)(gbase) + (voff)[_i]), (PG8_LAS unsigned*)(lds + (bufoff) + ldsw + _i * 8192), 16, 0, 0); } while (0)
; #define PG8_LDA(dst, b, h) do { _Pragma("unroll") for (int m = 0; m < 4; ++m) _Pragma("unroll") for (int k = 0; k < 2; ++k) dst[m][k] = *(const PG8_LAS bf16x8*)(lds + PG8_SA(b, h) + aoff + m * 2048 + k * 1024); } while (0)
; #define PG8_MMA(ai, bj, At, Bt) do { __builtin_amdgcn_s_setprio(1); _Pragma("unroll") for (int m = 0; m < 4; ++m) _Pragma("unroll") for (int n = 0; n < 2; ++n) _Pragma("unroll") for (int k = 0; k < 2; ++k) \
;         acc[ai][bj][m][n] = __builtin_amdgcn_mfma_f32_16x16x32_bf16(Bt[n][k], At[m][k], acc[ai][bj][m][n], 0, 0, 0); __builtin_amdgcn_s_setprio(0); } while (0)
; #define PG8_WAIT_V(n) asm volatile("s_waitcnt vmcnt(" #n ")" ::: "memory")
; #define PG8_WAIT_L(n) asm volatile("s_waitcnt lgkmcnt(" #n ")" ::: "memory")
; #define PG8_BAR __builtin_amdgcn_s_barrier()
; #define PG8_SCHED __builtin_amdgcn_sched_barrier(0)
; template <class Epi, class Sched, bool ALIGN_EPI = true>
; __device__ __forceinline__ void gemm_phase(PG8_LAS unsigned char* lds, const Gemm g, const Sched& S, const Epi& E, const int tid) {
;     ...
;             PG8_LDA(At, 1, 1); PG8_STAGE(PG8_SB(1, 0), b3, voffB); PG8_STAGE(PG8_SB(1, 1), b3 + hstepB, voffB); PG8_STAGE(PG8_SA(1, 0), a3, voffA);
;             PG8_WAIT_V(8); PG8_WAIT_L(0); PG8_BAR; PG8_MMA(1, 0, At, B0); PG8_MMA(1, 1, At, B1); PG8_BAR; PG8_SCHED;
;         }
;         if constexpr (ALIGN_EPI) { if (wr == 0) PG8_BAR; }
	s_add_i32 s15, s15, s67
	v_lshl_add_u64 v[196:197], v[200:201], 0, s[36:37]
	s_mov_b32 m0, s15
	ds_read_b128 v[140:143], v252 offset:49152
	ds_read_b128 v[152:155], v252 offset:50176
	ds_read_b128 v[156:159], v252 offset:51200
	ds_read_b128 v[168:171], v252 offset:52224
	ds_read_b128 v[172:175], v252 offset:53248
	ds_read_b128 v[184:187], v252 offset:54272
	ds_read_b128 v[188:191], v252 offset:55296
	ds_read_b128 v[192:195], v252 offset:56320
	global_load_lds_dwordx4 v[196:197], off
	s_add_i32 m0, s15, 0x2000
	s_add_u32 s22, s22, 0x20080
	v_lshl_add_u64 v[196:197], v[202:203], 0, s[36:37]
	s_addc_u32 s23, s23, 0
	s_add_i32 s15, s16, s67
	global_load_lds_dwordx4 v[196:197], off
	v_lshl_add_u64 v[196:197], s[22:23], 0, v[2:3]
	s_mov_b32 m0, s15
	s_nop 0
	global_load_lds_dwordx4 v[196:197], off
	v_lshl_add_u64 v[196:197], s[22:23], 0, v[210:211]
	s_add_i32 m0, s15, 0x2000
	s_nop 0
	global_load_lds_dwordx4 v[196:197], off
	v_lshl_add_u64 v[196:197], v[204:205], 0, s[36:37]
	s_mov_b32 m0, s75
	s_nop 0
	global_load_lds_dwordx4 v[196:197], off
	v_lshl_add_u64 v[196:197], v[206:207], 0, s[36:37]
	s_mov_b32 m0, s76
	s_nop 0
	global_load_lds_dwordx4 v[196:197], off
	s_waitcnt vmcnt(8)
	s_waitcnt lgkmcnt(0)
	s_barrier
	s_waitcnt lgkmcnt(0)
	v_mfma_f32_16x16x32_bf16 v[80:83], v[60:63], v[140:143], v[80:83]
	v_mfma_f32_16x16x32_bf16 v[80:83], v[64:67], v[152:155], v[80:83]
	v_mfma_f32_16x16x32_bf16 v[76:79], v[68:71], v[140:143], v[76:79]
	v_mfma_f32_16x16x32_bf16 v[76:79], v[72:75], v[152:155], v[76:79]
	v_mfma_f32_16x16x32_bf16 v[48:51], v[60:63], v[156:159], v[48:51]
	v_mfma_f32_16x16x32_bf16 v[48:51], v[64:67], v[168:171], v[48:51]
	v_mfma_f32_16x16x32_bf16 v[44:47], v[68:71], v[156:159], v[44:47]
	v_mfma_f32_16x16x32_bf16 v[44:47], v[72:75], v[168:171], v[44:47]
	v_mfma_f32_16x16x32_bf16 v[32:35], v[60:63], v[172:175], v[32:35]
	v_mfma_f32_16x16x32_bf16 v[32:35], v[64:67], v[184:187], v[32:35]
	v_mfma_f32_16x16x32_bf16 v[28:31], v[68:71], v[172:175], v[28:31]
	v_mfma_f32_16x16x32_bf16 v[28:31], v[72:75], v[184:187], v[28:31]
	v_mfma_f32_16x16x32_bf16 v[16:19], v[60:63], v[188:191], v[16:19]
	v_mfma_f32_16x16x32_bf16 v[16:19], v[64:67], v[192:195], v[16:19]
	v_mfma_f32_16x16x32_bf16 v[12:15], v[68:71], v[188:191], v[12:15]
	v_mfma_f32_16x16x32_bf16 v[12:15], v[72:75], v[192:195], v[12:15]
	v_mfma_f32_16x16x32_bf16 v[56:59], v[100:103], v[140:143], v[56:59]
	v_mfma_f32_16x16x32_bf16 v[56:59], v[112:115], v[152:155], v[56:59]
	v_mfma_f32_16x16x32_bf16 v[52:55], v[116:119], v[140:143], v[52:55]
	v_mfma_f32_16x16x32_bf16 v[52:55], v[136:139], v[152:155], v[52:55]
	v_mfma_f32_16x16x32_bf16 v[40:43], v[100:103], v[156:159], v[40:43]
	v_mfma_f32_16x16x32_bf16 v[40:43], v[112:115], v[168:171], v[40:43]
	v_mfma_f32_16x16x32_bf16 v[36:39], v[116:119], v[156:159], v[36:39]
	v_mfma_f32_16x16x32_bf16 v[36:39], v[136:139], v[168:171], v[36:39]
	v_mfma_f32_16x16x32_bf16 v[24:27], v[100:103], v[172:175], v[24:27]
	v_mfma_f32_16x16x32_bf16 v[24:27], v[112:115], v[184:187], v[24:27]
	v_mfma_f32_16x16x32_bf16 v[20:23], v[116:119], v[172:175], v[20:23]
	v_mfma_f32_16x16x32_bf16 v[20:23], v[136:139], v[184:187], v[20:23]
	v_mfma_f32_16x16x32_bf16 v[8:11], v[100:103], v[188:191], v[8:11]
	v_mfma_f32_16x16x32_bf16 v[8:11], v[112:115], v[192:195], v[8:11]
	v_mfma_f32_16x16x32_bf16 v[4:7], v[116:119], v[188:191], v[4:7]
	v_mfma_f32_16x16x32_bf16 v[4:7], v[136:139], v[192:195], v[4:7]
	s_barrier
	s_add_i32 s53, s53, 2
	s_add_u32 s12, s12, 0x100
	s_addc_u32 s13, s13, 0
	s_add_u32 s20, s20, 0x100
	s_addc_u32 s21, s21, 0
	s_cmp_gt_u32 s53, 5
	s_cbranch_scc0 .LBB0_426
	s_and_b64 vcc, exec, s[48:49]
	s_cbranch_vccz .LBB0_429
	s_barrier

; #define PG8_STAGE(bufoff, gbase, voff) do { _Pragma("unroll") for (int _i = 0; _i < 2; ++_i) \
;         __builtin_amdgcn_global_load_lds((const unsigned*)((const char*)(gbase) + (voff)[_i]), (PG8_LAS unsigned*)(lds + (bufoff) + ldsw + _i * 8192), 16, 0, 0); } while (0)
; #define PG8_LDA(dst, b, h) do { _Pragma("unroll") for (int m = 0; m < 4; ++m) _Pragma("unroll") for (int k = 0; k < 2; ++k) dst[m][k] = *(const PG8_LAS bf16x8*)(lds + PG8_SA(b, h) + aoff + m * 2048 + k * 1024); } while (0)
; #define PG8_LDB(dst, b, h) do { _Pragma("unroll") for (int n = 0; n < 2; ++n) _Pragma("unroll") for (int k = 0; k < 2; ++k) dst[n][k] = *(const PG8_LAS bf16x8*)(lds + PG8_SB(b, h) + boff + n * 2048 + k * 1024); } while (0)
; #define PG8_MMA(ai, bj, At, Bt) do { __builtin_amdgcn_s_setprio(1); _Pragma("unroll") for (int m = 0; m < 4; ++m) _Pragma("unroll") for (int n = 0; n < 2; ++n) _Pragma("unroll") for (int k = 0; k < 2; ++k) \
;         acc[ai][bj][m][n] = __builtin_amdgcn_mfma_f32_16x16x32_bf16(Bt[n][k], At[m][k], acc[ai][bj][m][n], 0, 0, 0); __builtin_amdgcn_s_setprio(0); } while (0)
; #define PG8_WAIT_V(n) asm volatile("s_waitcnt vmcnt(" #n ")" ::: "memory")
; #define PG8_WAIT_L(n) asm volatile("s_waitcnt lgkmcnt(" #n ")" ::: "memory")
; template <class Epi, class Sched, bool ALIGN_EPI = true>
; __device__ __forceinline__ void gemm_phase(PG8_LAS unsigned char* lds, const Gemm g, const Sched& S, const Epi& E, const int tid) {
;     ...
;         for (int t = 0; t < nt; t += 2) {
;             const bool last = (t == nt - 2);
;             const char* a1 = cA + (size_t)(t + 1) * kstep;
;             const char* a2 = last ? nA : cA + (size_t)(t + 2) * kstep; const char* b2 = last ? nB : cB + (size_t)(t + 2) * kstep;
;             const char* a3 = a2 + kstep; const char* b3 = b2 + kstep;
;             if (last && has_next) S.a_ready(nxt);
;             PG8_LDB(B0, 0, 0); PG8_LDB(B1, 0, 1); PG8_SCHED; PG8_LDA(At, 0, 0); PG8_STAGE(PG8_SA(1, 1), a1 + hstepA, voffA);
;             PG8_WAIT_V(8); PG8_WAIT_L(0); PG8_BAR; PG8_MMA(0, 0, At, B0); PG8_MMA(0, 1, At, B1); PG8_BAR; PG8_SCHED;
;             PG8_LDA(At, 0, 1); PG8_STAGE(PG8_SB(0, 0), b2, voffB); PG8_STAGE(PG8_SB(0, 1), b2 + hstepB, voffB); PG8_STAGE(PG8_SA(0, 0), a2, voffA);
;             PG8_WAIT_V(8); PG8_WAIT_L(0); PG8_BAR; PG8_MMA(1, 0, At, B0); PG8_MMA(1, 1, At, B1); PG8_BAR; PG8_SCHED;
.LBB0_514:
	s_add_u32 s44, s42, 0xfff80080
	s_addc_u32 s45, s43, -1
	s_add_i32 s57, 0, 0x10000
	s_cmp_eq_u32 s56, 28
	s_cselect_b32 s47, s13, s45
	s_cselect_b32 s46, s52, s44
	s_cselect_b32 s45, s23, s55
	s_cselect_b32 s44, s53, s54
	s_add_i32 s60, 0, 0x14000
	v_add_u32_e32 v158, s57, v147
	v_add_u32_e32 v174, s60, v147
	ds_read_b128 v[142:145], v158
	ds_read_b128 v[150:153], v158 offset:1024
	ds_read_b128 v[154:157], v158 offset:2048
	ds_read_b128 v[158:161], v158 offset:3072
	ds_read_b128 v[162:165], v174
	ds_read_b128 v[166:169], v174 offset:1024
	ds_read_b128 v[170:173], v174 offset:2048
	ds_read_b128 v[174:177], v174 offset:3072
	v_lshl_add_u64 v[206:207], s[42:43], 0, v[138:139]
	s_add_i32 m0, s7, 0xc000
	ds_read_b128 v[178:181], v149
	ds_read_b128 v[182:185], v149 offset:1024
	ds_read_b128 v[186:189], v149 offset:2048
	ds_read_b128 v[190:193], v149 offset:3072
	ds_read_b128 v[194:197], v149 offset:4096
	ds_read_b128 v[198:201], v149 offset:5120
	ds_read_b128 v[202:205], v149 offset:6144
	ds_read_b128 v[210:213], v149 offset:7168
	global_load_lds_dwordx4 v[206:207], off
	v_lshl_add_u64 v[206:207], s[42:43], 0, v[140:141]
	s_add_i32 m0, s7, 0xe000
	s_nop 0
	global_load_lds_dwordx4 v[206:207], off
	s_waitcnt vmcnt(8)
	s_waitcnt lgkmcnt(0)
	s_barrier
	s_waitcnt lgkmcnt(0)
	v_mfma_f32_16x16x32_bf16 v[128:131], v[142:145], v[178:181], v[128:131]
	v_mfma_f32_16x16x32_bf16 v[128:131], v[150:153], v[182:185], v[128:131]
	v_mfma_f32_16x16x32_bf16 v[124:127], v[154:157], v[178:181], v[124:127]
	v_mfma_f32_16x16x32_bf16 v[124:127], v[158:161], v[182:185], v[124:127]
	v_mfma_f32_16x16x32_bf16 v[120:123], v[142:145], v[186:189], v[120:123]
	v_mfma_f32_16x16x32_bf16 v[120:123], v[150:153], v[190:193], v[120:123]
	v_mfma_f32_16x16x32_bf16 v[112:115], v[154:157], v[186:189], v[112:115]
	v_mfma_f32_16x16x32_bf16 v[112:115], v[158:161], v[190:193], v[112:115]
	v_mfma_f32_16x16x32_bf16 v[104:107], v[142:145], v[194:197], v[104:107]
	v_mfma_f32_16x16x32_bf16 v[104:107], v[150:153], v[198:201], v[104:107]
	v_mfma_f32_16x16x32_bf16 v[96:99], v[154:157], v[194:197], v[96:99]
	v_mfma_f32_16x16x32_bf16 v[96:99], v[158:161], v[198:201], v[96:99]
	v_mfma_f32_16x16x32_bf16 v[88:91], v[142:145], v[202:205], v[88:91]
	v_mfma_f32_16x16x32_bf16 v[88:91], v[150:153], v[210:213], v[88:91]
	v_mfma_f32_16x16x32_bf16 v[80:83], v[154:157], v[202:205], v[80:83]
	v_mfma_f32_16x16x32_bf16 v[80:83], v[158:161], v[210:213], v[80:83]
	v_mfma_f32_16x16x32_bf16 v[116:119], v[162:165], v[178:181], v[116:119]
	v_mfma_f32_16x16x32_bf16 v[116:119], v[166:169], v[182:185], v[116:119]
	v_mfma_f32_16x16x32_bf16 v[108:111], v[170:173], v[178:181], v[108:111]
	v_mfma_f32_16x16x32_bf16 v[108:111], v[174:177], v[182:185], v[108:111]
	v_mfma_f32_16x16x32_bf16 v[100:103], v[162:165], v[186:189], v[100:103]
	v_mfma_f32_16x16x32_bf16 v[100:103], v[166:169], v[190:193], v[100:103]
	v_mfma_f32_16x16x32_bf16 v[92:95], v[170:173], v[186:189], v[92:95]
	v_mfma_f32_16x16x32_bf16 v[92:95], v[174:177], v[190:193], v[92:95]
	v_mfma_f32_16x16x32_bf16 v[84:87], v[162:165], v[194:197], v[84:87]
	v_mfma_f32_16x16x32_bf16 v[84:87], v[166:169], v[198:201], v[84:87]
	v_mfma_f32_16x16x32_bf16 v[76:79], v[170:173], v[194:197], v[76:79]
	v_mfma_f32_16x16x32_bf16 v[76:79], v[174:177], v[198:201], v[76:79]
	v_mfma_f32_16x16x32_bf16 v[72:75], v[162:165], v[202:205], v[72:75]
	v_mfma_f32_16x16x32_bf16 v[72:75], v[166:169], v[210:213], v[72:75]
	v_mfma_f32_16x16x32_bf16 v[68:71], v[170:173], v[202:205], v[68:71]
	v_mfma_f32_16x16x32_bf16 v[68:71], v[174:177], v[210:213], v[68:71]
	s_barrier
	s_add_i32 s57, s57, s21
	v_lshl_add_u64 v[206:207], s[44:45], 0, v[2:3]
	s_mov_b32 m0, s57
	ds_read_b128 v[178:181], v149 offset:16384
	ds_read_b128 v[182:185], v149 offset:17408
	ds_read_b128 v[186:189], v149 offset:18432
	ds_read_b128 v[190:193], v149 offset:19456
	ds_read_b128 v[194:197], v149 offset:20480
	ds_read_b128 v[198:201], v149 offset:21504
	ds_read_b128 v[202:205], v149 offset:22528
	ds_read_b128 v[210:213], v149 offset:23552
	global_load_lds_dwordx4 v[206:207], off
	s_add_i32 m0, s57, 0x2000
	s_add_u32 s58, s44, 0x80000
	v_lshl_add_u64 v[214:215], s[44:45], 0, v[132:133]
	s_addc_u32 s59, s45, 0
	s_add_i32 s57, s60, s21
	global_load_lds_dwordx4 v[214:215], off
	v_lshl_add_u64 v[216:217], s[58:59], 0, v[2:3]
	s_mov_b32 m0, s57
	v_lshl_add_u64 v[218:219], s[46:47], 0, v[134:135]
	global_load_lds_dwordx4 v[216:217], off
	v_lshl_add_u64 v[216:217], s[58:59], 0, v[132:133]
	s_add_i32 m0, s57, 0x2000
	s_nop 0
	global_load_lds_dwordx4 v[216:217], off
	v_lshl_add_u64 v[216:217], s[46:47], 0, v[136:137]
	s_mov_b32 m0, s7
	s_nop 0
	global_load_lds_dwordx4 v[216:217], off
	s_mov_b32 m0, s11
	s_nop 0
	global_load_lds_dwordx4 v[218:219], off
	s_waitcnt vmcnt(8)
	s_waitcnt lgkmcnt(0)
	s_barrier
; #define PG8_STAGE(bufoff, gbase, voff) do { _Pragma("unroll") for (int _i = 0; _i < 2; ++_i) \
;         __builtin_amdgcn_global_load_lds((const unsigned*)((const char*)(gbase) + (voff)[_i]), (PG8_LAS unsigned*)(lds + (bufoff) + ldsw + _i * 8192), 16, 0, 0); } while (0)
; #define PG8_LDA(dst, b, h) do { _Pragma("unroll") for (int m = 0; m < 4; ++m) _Pragma("unroll") for (int k = 0; k < 2; ++k) dst[m][k] = *(const PG8_LAS bf16x8*)(lds + PG8_SA(b, h) + aoff + m * 2048 + k * 1024); } while (0)
; #define PG8_LDB(dst, b, h) do { _Pragma("unroll") for (int n = 0; n < 2; ++n) _Pragma("unroll") for (int k = 0; k < 2; ++k) dst[n][k] = *(const PG8_LAS bf16x8*)(lds + PG8_SB(b, h) + boff + n * 2048 + k * 1024); } while (0)
; #define PG8_MMA(ai, bj, At, Bt) do { __builtin_amdgcn_s_setprio(1); _Pragma("unroll") for (int m = 0; m < 4; ++m) _Pragma("unroll") for (int n = 0; n < 2; ++n) _Pragma("unroll") for (int k = 0; k < 2; ++k) \
;         acc[ai][bj][m][n] = __builtin_amdgcn_mfma_f32_16x16x32_bf16(Bt[n][k], At[m][k], acc[ai][bj][m][n], 0, 0, 0); __builtin_amdgcn_s_setprio(0); } while (0)
; #define PG8_WAIT_V(n) asm volatile("s_waitcnt vmcnt(" #n ")" ::: "memory")
; #define PG8_WAIT_L(n) asm volatile("s_waitcnt lgkmcnt(" #n ")" ::: "memory")
; #define PG8_BAR __builtin_amdgcn_s_barrier()
; #define PG8_SCHED __builtin_amdgcn_sched_barrier(0)
; template <class Epi, class Sched, bool ALIGN_EPI = true>
; __device__ __forceinline__ void gemm_phase(PG8_LAS unsigned char* lds, const Gemm g, const Sched& S, const Epi& E, const int tid) {
;     ...
;             PG8_WAIT_V(8); PG8_WAIT_L(0); PG8_BAR; PG8_MMA(1, 0, At, B0); PG8_MMA(1, 1, At, B1); PG8_BAR; PG8_SCHED;
;             PG8_LDB(B0, 1, 0); PG8_LDB(B1, 1, 1); PG8_SCHED; PG8_LDA(At, 1, 0); PG8_STAGE(PG8_SA(0, 1), a2 + hstepA, voffA);
;             PG8_WAIT_V(8); PG8_WAIT_L(0); PG8_BAR; PG8_MMA(0, 0, At, B0); PG8_MMA(0, 1, At, B1); PG8_BAR; PG8_SCHED;
	s_waitcnt lgkmcnt(0)
	v_mfma_f32_16x16x32_bf16 v[64:67], v[142:145], v[178:181], v[64:67]
	v_mfma_f32_16x16x32_bf16 v[64:67], v[150:153], v[182:185], v[64:67]
	v_mfma_f32_16x16x32_bf16 v[60:63], v[154:157], v[178:181], v[60:63]
	v_mfma_f32_16x16x32_bf16 v[60:63], v[158:161], v[182:185], v[60:63]
	v_mfma_f32_16x16x32_bf16 v[56:59], v[142:145], v[186:189], v[56:59]
	v_mfma_f32_16x16x32_bf16 v[56:59], v[150:153], v[190:193], v[56:59]
	v_mfma_f32_16x16x32_bf16 v[48:51], v[154:157], v[186:189], v[48:51]
	v_mfma_f32_16x16x32_bf16 v[48:51], v[158:161], v[190:193], v[48:51]
	v_mfma_f32_16x16x32_bf16 v[40:43], v[142:145], v[194:197], v[40:43]
	v_mfma_f32_16x16x32_bf16 v[40:43], v[150:153], v[198:201], v[40:43]
	v_mfma_f32_16x16x32_bf16 v[32:35], v[154:157], v[194:197], v[32:35]
	v_mfma_f32_16x16x32_bf16 v[32:35], v[158:161], v[198:201], v[32:35]
	v_mfma_f32_16x16x32_bf16 v[24:27], v[142:145], v[202:205], v[24:27]
	v_mfma_f32_16x16x32_bf16 v[24:27], v[150:153], v[210:213], v[24:27]
	v_mfma_f32_16x16x32_bf16 v[16:19], v[154:157], v[202:205], v[16:19]
	v_mfma_f32_16x16x32_bf16 v[16:19], v[158:161], v[210:213], v[16:19]
	v_mfma_f32_16x16x32_bf16 v[52:55], v[162:165], v[178:181], v[52:55]
	v_mfma_f32_16x16x32_bf16 v[52:55], v[166:169], v[182:185], v[52:55]
	v_mfma_f32_16x16x32_bf16 v[44:47], v[170:173], v[178:181], v[44:47]
	v_mfma_f32_16x16x32_bf16 v[44:47], v[174:177], v[182:185], v[44:47]
	v_mfma_f32_16x16x32_bf16 v[36:39], v[162:165], v[186:189], v[36:39]
	v_mfma_f32_16x16x32_bf16 v[36:39], v[166:169], v[190:193], v[36:39]
	v_mfma_f32_16x16x32_bf16 v[28:31], v[170:173], v[186:189], v[28:31]
	v_mfma_f32_16x16x32_bf16 v[28:31], v[174:177], v[190:193], v[28:31]
	v_mfma_f32_16x16x32_bf16 v[20:23], v[162:165], v[194:197], v[20:23]
	v_mfma_f32_16x16x32_bf16 v[20:23], v[166:169], v[198:201], v[20:23]
	v_mfma_f32_16x16x32_bf16 v[12:15], v[170:173], v[194:197], v[12:15]
	v_mfma_f32_16x16x32_bf16 v[12:15], v[174:177], v[198:201], v[12:15]
	v_mfma_f32_16x16x32_bf16 v[8:11], v[162:165], v[202:205], v[8:11]
	v_mfma_f32_16x16x32_bf16 v[8:11], v[166:169], v[210:213], v[8:11]
	v_mfma_f32_16x16x32_bf16 v[4:7], v[170:173], v[202:205], v[4:7]
	v_mfma_f32_16x16x32_bf16 v[4:7], v[174:177], v[210:213], v[4:7]
	s_barrier
	s_add_i32 s57, 0, 0x18000
	s_add_i32 s58, 0, 0x1c000
	v_add_u32_e32 v158, s57, v147
	v_add_u32_e32 v174, s58, v147
	ds_read_b128 v[142:145], v158
	ds_read_b128 v[150:153], v158 offset:1024
	ds_read_b128 v[154:157], v158 offset:2048
	ds_read_b128 v[158:161], v158 offset:3072
	ds_read_b128 v[162:165], v174
	ds_read_b128 v[166:169], v174 offset:1024
	ds_read_b128 v[170:173], v174 offset:2048
	ds_read_b128 v[174:177], v174 offset:3072
	s_add_u32 s46, s46, 0x80000
	s_addc_u32 s47, s47, 0
	s_mov_b32 m0, s30
	v_lshl_add_u64 v[220:221], s[46:47], 0, v[136:137]
	ds_read_b128 v[178:181], v149 offset:32768
	ds_read_b128 v[182:185], v149 offset:33792
	ds_read_b128 v[186:189], v149 offset:34816
	ds_read_b128 v[190:193], v149 offset:35840
	ds_read_b128 v[194:197], v149 offset:36864
	ds_read_b128 v[198:201], v149 offset:37888
	ds_read_b128 v[202:205], v149 offset:38912
	ds_read_b128 v[210:213], v149 offset:39936
	global_load_lds_dwordx4 v[220:221], off
	v_lshl_add_u64 v[220:221], s[46:47], 0, v[134:135]
	s_mov_b32 m0, s48
	s_nop 0
	global_load_lds_dwordx4 v[220:221], off
	s_waitcnt vmcnt(8)
	s_waitcnt lgkmcnt(0)
	s_barrier
	s_waitcnt lgkmcnt(0)
	v_mfma_f32_16x16x32_bf16 v[128:131], v[142:145], v[178:181], v[128:131]
	v_mfma_f32_16x16x32_bf16 v[128:131], v[150:153], v[182:185], v[128:131]
	v_mfma_f32_16x16x32_bf16 v[124:127], v[154:157], v[178:181], v[124:127]
	v_mfma_f32_16x16x32_bf16 v[124:127], v[158:161], v[182:185], v[124:127]
	v_mfma_f32_16x16x32_bf16 v[120:123], v[142:145], v[186:189], v[120:123]
	v_mfma_f32_16x16x32_bf16 v[120:123], v[150:153], v[190:193], v[120:123]
	v_mfma_f32_16x16x32_bf16 v[112:115], v[154:157], v[186:189], v[112:115]
	v_mfma_f32_16x16x32_bf16 v[112:115], v[158:161], v[190:193], v[112:115]
	v_mfma_f32_16x16x32_bf16 v[104:107], v[142:145], v[194:197], v[104:107]
	v_mfma_f32_16x16x32_bf16 v[104:107], v[150:153], v[198:201], v[104:107]
	v_mfma_f32_16x16x32_bf16 v[96:99], v[154:157], v[194:197], v[96:99]
	v_mfma_f32_16x16x32_bf16 v[96:99], v[158:161], v[198:201], v[96:99]
	v_mfma_f32_16x16x32_bf16 v[88:91], v[142:145], v[202:205], v[88:91]
	v_mfma_f32_16x16x32_bf16 v[88:91], v[150:153], v[210:213], v[88:91]
	v_mfma_f32_16x16x32_bf16 v[80:83], v[154:157], v[202:205], v[80:83]
	v_mfma_f32_16x16x32_bf16 v[80:83], v[158:161], v[210:213], v[80:83]
	v_mfma_f32_16x16x32_bf16 v[116:119], v[162:165], v[178:181], v[116:119]
	v_mfma_f32_16x16x32_bf16 v[116:119], v[166:169], v[182:185], v[116:119]
	v_mfma_f32_16x16x32_bf16 v[108:111], v[170:173], v[178:181], v[108:111]
	v_mfma_f32_16x16x32_bf16 v[108:111], v[174:177], v[182:185], v[108:111]
	v_mfma_f32_16x16x32_bf16 v[100:103], v[162:165], v[186:189], v[100:103]
	v_mfma_f32_16x16x32_bf16 v[100:103], v[166:169], v[190:193], v[100:103]
	v_mfma_f32_16x16x32_bf16 v[92:95], v[170:173], v[186:189], v[92:95]
	v_mfma_f32_16x16x32_bf16 v[92:95], v[174:177], v[190:193], v[92:95]
	v_mfma_f32_16x16x32_bf16 v[84:87], v[162:165], v[194:197], v[84:87]
	v_mfma_f32_16x16x32_bf16 v[84:87], v[166:169], v[198:201], v[84:87]
	v_mfma_f32_16x16x32_bf16 v[76:79], v[170:173], v[194:197], v[76:79]
	v_mfma_f32_16x16x32_bf16 v[76:79], v[174:177], v[198:201], v[76:79]
	v_mfma_f32_16x16x32_bf16 v[72:75], v[162:165], v[202:205], v[72:75]
	v_mfma_f32_16x16x32_bf16 v[72:75], v[166:169], v[210:213], v[72:75]
	v_mfma_f32_16x16x32_bf16 v[68:71], v[170:173], v[202:205], v[68:71]
	v_mfma_f32_16x16x32_bf16 v[68:71], v[174:177], v[210:213], v[68:71]
	s_barrier
; #define PG8_STAGE(bufoff, gbase, voff) do { _Pragma("unroll") for (int _i = 0; _i < 2; ++_i) \
;         __builtin_amdgcn_global_load_lds((const unsigned*)((const char*)(gbase) + (voff)[_i]), (PG8_LAS unsigned*)(lds + (bufoff) + ldsw + _i * 8192), 16, 0, 0); } while (0)
; #define PG8_LDA(dst, b, h) do { _Pragma("unroll") for (int m = 0; m < 4; ++m) _Pragma("unroll") for (int k = 0; k < 2; ++k) dst[m][k] = *(const PG8_LAS bf16x8*)(lds + PG8_SA(b, h) + aoff + m * 2048 + k * 1024); } while (0)
; #define PG8_MMA(ai, bj, At, Bt) do { __builtin_amdgcn_s_setprio(1); _Pragma("unroll") for (int m = 0; m < 4; ++m) _Pragma("unroll") for (int n = 0; n < 2; ++n) _Pragma("unroll") for (int k = 0; k < 2; ++k) \
;         acc[ai][bj][m][n] = __builtin_amdgcn_mfma_f32_16x16x32_bf16(Bt[n][k], At[m][k], acc[ai][bj][m][n], 0, 0, 0); __builtin_amdgcn_s_setprio(0); } while (0)
; #define PG8_WAIT_V(n) asm volatile("s_waitcnt vmcnt(" #n ")" ::: "memory")
; #define PG8_WAIT_L(n) asm volatile("s_waitcnt lgkmcnt(" #n ")" ::: "memory")
; #define PG8_BAR __builtin_amdgcn_s_barrier()
; #define PG8_SCHED __builtin_amdgcn_sched_barrier(0)
; template <class Epi, class Sched, bool ALIGN_EPI = true>
; __device__ __forceinline__ void gemm_phase(PG8_LAS unsigned char* lds, const Gemm g, const Sched& S, const Epi& E, const int tid) {
;     ...
;             PG8_LDA(At, 1, 1); PG8_STAGE(PG8_SB(1, 0), b3, voffB); PG8_STAGE(PG8_SB(1, 1), b3 + hstepB, voffB); PG8_STAGE(PG8_SA(1, 0), a3, voffA);
;             PG8_WAIT_V(8); PG8_WAIT_L(0); PG8_BAR; PG8_MMA(1, 0, At, B0); PG8_MMA(1, 1, At, B1); PG8_BAR; PG8_SCHED;
;         }
;         if constexpr (ALIGN_EPI) { if (wr == 0) PG8_BAR; }
	s_add_i32 s46, s57, s21
	v_lshl_add_u64 v[206:207], v[206:207], 0, s[36:37]
	s_mov_b32 m0, s46
	ds_read_b128 v[178:181], v149 offset:49152
	ds_read_b128 v[182:185], v149 offset:50176
	ds_read_b128 v[186:189], v149 offset:51200
	ds_read_b128 v[190:193], v149 offset:52224
	ds_read_b128 v[194:197], v149 offset:53248
	ds_read_b128 v[198:201], v149 offset:54272
	ds_read_b128 v[202:205], v149 offset:55296
	ds_read_b128 v[210:213], v149 offset:56320
	global_load_lds_dwordx4 v[206:207], off
	s_add_i32 m0, s46, 0x2000
	s_add_u32 s44, s44, 0x80080
	v_lshl_add_u64 v[206:207], v[214:215], 0, s[36:37]
	s_addc_u32 s45, s45, 0
	s_add_i32 s46, s58, s21
	global_load_lds_dwordx4 v[206:207], off
	v_lshl_add_u64 v[206:207], s[44:45], 0, v[2:3]
	s_mov_b32 m0, s46
	s_nop 0
	global_load_lds_dwordx4 v[206:207], off
	v_lshl_add_u64 v[206:207], s[44:45], 0, v[132:133]
	s_add_i32 m0, s46, 0x2000
	s_nop 0
	global_load_lds_dwordx4 v[206:207], off
	v_lshl_add_u64 v[206:207], v[216:217], 0, s[36:37]
	s_mov_b32 m0, s49
	s_nop 0
	global_load_lds_dwordx4 v[206:207], off
	v_lshl_add_u64 v[206:207], v[218:219], 0, s[36:37]
	s_mov_b32 m0, s50
	s_nop 0
	global_load_lds_dwordx4 v[206:207], off
	s_waitcnt vmcnt(8)
	s_waitcnt lgkmcnt(0)
	s_barrier
	s_waitcnt lgkmcnt(0)
	v_mfma_f32_16x16x32_bf16 v[64:67], v[142:145], v[178:181], v[64:67]
	v_mfma_f32_16x16x32_bf16 v[64:67], v[150:153], v[182:185], v[64:67]
	v_mfma_f32_16x16x32_bf16 v[60:63], v[154:157], v[178:181], v[60:63]
	v_mfma_f32_16x16x32_bf16 v[60:63], v[158:161], v[182:185], v[60:63]
	v_mfma_f32_16x16x32_bf16 v[56:59], v[142:145], v[186:189], v[56:59]
	v_mfma_f32_16x16x32_bf16 v[56:59], v[150:153], v[190:193], v[56:59]
	v_mfma_f32_16x16x32_bf16 v[48:51], v[154:157], v[186:189], v[48:51]
	v_mfma_f32_16x16x32_bf16 v[48:51], v[158:161], v[190:193], v[48:51]
	v_mfma_f32_16x16x32_bf16 v[40:43], v[142:145], v[194:197], v[40:43]
	v_mfma_f32_16x16x32_bf16 v[40:43], v[150:153], v[198:201], v[40:43]
	v_mfma_f32_16x16x32_bf16 v[32:35], v[154:157], v[194:197], v[32:35]
	v_mfma_f32_16x16x32_bf16 v[32:35], v[158:161], v[198:201], v[32:35]
	v_mfma_f32_16x16x32_bf16 v[24:27], v[142:145], v[202:205], v[24:27]
	v_mfma_f32_16x16x32_bf16 v[24:27], v[150:153], v[210:213], v[24:27]
	v_mfma_f32_16x16x32_bf16 v[16:19], v[154:157], v[202:205], v[16:19]
	v_mfma_f32_16x16x32_bf16 v[16:19], v[158:161], v[210:213], v[16:19]
	v_mfma_f32_16x16x32_bf16 v[52:55], v[162:165], v[178:181], v[52:55]
	v_mfma_f32_16x16x32_bf16 v[52:55], v[166:169], v[182:185], v[52:55]
	v_mfma_f32_16x16x32_bf16 v[44:47], v[170:173], v[178:181], v[44:47]
	v_mfma_f32_16x16x32_bf16 v[44:47], v[174:177], v[182:185], v[44:47]
	v_mfma_f32_16x16x32_bf16 v[36:39], v[162:165], v[186:189], v[36:39]
	v_mfma_f32_16x16x32_bf16 v[36:39], v[166:169], v[190:193], v[36:39]
	v_mfma_f32_16x16x32_bf16 v[28:31], v[170:173], v[186:189], v[28:31]
	v_mfma_f32_16x16x32_bf16 v[28:31], v[174:177], v[190:193], v[28:31]
	v_mfma_f32_16x16x32_bf16 v[20:23], v[162:165], v[194:197], v[20:23]
	v_mfma_f32_16x16x32_bf16 v[20:23], v[166:169], v[198:201], v[20:23]
	v_mfma_f32_16x16x32_bf16 v[12:15], v[170:173], v[194:197], v[12:15]
	v_mfma_f32_16x16x32_bf16 v[12:15], v[174:177], v[198:201], v[12:15]
	v_mfma_f32_16x16x32_bf16 v[8:11], v[162:165], v[202:205], v[8:11]
	v_mfma_f32_16x16x32_bf16 v[8:11], v[166:169], v[210:213], v[8:11]
	v_mfma_f32_16x16x32_bf16 v[4:7], v[170:173], v[202:205], v[4:7]
	v_mfma_f32_16x16x32_bf16 v[4:7], v[174:177], v[210:213], v[4:7]
	s_barrier
	s_add_i32 s56, s56, 2
	s_add_u32 s42, s42, 0x100
	s_addc_u32 s43, s43, 0
	s_add_u32 s54, s54, 0x100
	s_addc_u32 s55, s55, 0
	s_cmp_gt_u32 s56, 29
	s_cbranch_scc0 .LBB0_514
; __device__ __forceinline__ unsigned cvt_pk_bf16(float lo, float hi) { unsigned r; asm volatile("v_cvt_pk_bf16_f32 %0, %1, %2" : "=v"(r) : "v"(lo), "v"(hi)); return r; }
; #define PG8_WAIT_V(n) asm volatile("s_waitcnt vmcnt(" #n ")" ::: "memory")
; #define PG8_BAR __builtin_amdgcn_s_barrier()
;     __device__ __forceinline__ void operator()(const f32x4 (&acc)[2][2][4][2], const Unit& u, int wr, int wc, int fr, int fq) const {
;         const int row0 = u.pm * BM + wr * 64 + fr; const int col0 = u.pn * BM + wc * 32 + 8 * fq;
; #pragma unroll
;         for (int ai = 0; ai < 2; ++ai)
; #pragma unroll
;             for (int m = 0; m < 4; ++m) { bf16_t* rowp = O + (size_t)(row0 + ai * HALF + m * 16) * ldc + col0;
; #pragma unroll
;                 for (int bj = 0; bj < 2; ++bj) { const f32x4 v0 = acc[ai][bj][m][0], v1 = acc[ai][bj][m][1];
;                     u32x4 w; w.x = cvt_pk_bf16(v0[0], v0[1]); w.y = cvt_pk_bf16(v0[2], v0[3]); w.z = cvt_pk_bf16(v1[0], v1[1]); w.w = cvt_pk_bf16(v1[2], v1[3]);
;                     *(u32x4*)(rowp + bj * HALF) = w; } }
; template <class Epi, class Sched, bool ALIGN_EPI = true>
; __device__ __forceinline__ void gemm_phase(PG8_LAS unsigned char* lds, const Gemm g, const Sched& S, const Epi& E, const int tid) {
;     ...
;         if (!has_next) break;
; #pragma unroll
;         for (int a = 0; a < 2; ++a)
; #pragma unroll
;             for (int b = 0; b < 2; ++b)
; #pragma unroll
;                 for (int m = 0; m < 4; ++m)
; #pragma unroll
;                     for (int n = 0; n < 2; ++n) acc[a][b][m][n] = (f32x4){0.f, 0.f, 0.f, 0.f};
;         cur = nxt; cA = nA; cB = nB; ++ui;
;         if constexpr (ALIGN_EPI) { if (wr == 1) PG8_BAR; }
;     }
;     PG8_WAIT_V(0);
;     if constexpr (!ALIGN_EPI) { if (wr == 0) PG8_BAR; }
;     PG8_BAR;
	v_lshl_or_b32 v144, s10, 8, v148
	v_lshl_add_u32 v152, s6, 8, v146
	v_ashrrev_i32_e32 v145, 31, v144
	v_mov_b64_e32 v[142:143], s[0:1]
	s_movk_i32 s3, 0x3200
	v_mad_i64_i32 v[150:151], s[42:43], v152, s3, v[142:143]
	v_lshlrev_b64 v[144:145], 1, v[144:145]
	v_lshl_add_u64 v[150:151], v[150:151], 0, v[144:145]
	v_cvt_pk_bf16_f32 v128, v128, v129
	v_cvt_pk_bf16_f32 v129, v130, v131
	v_cvt_pk_bf16_f32 v130, v124, v125
	v_cvt_pk_bf16_f32 v131, v126, v127
	global_store_dwordx4 v[150:151], v[128:131], off
	v_cvt_pk_bf16_f32 v116, v116, v117
	v_cvt_pk_bf16_f32 v117, v118, v119
	v_cvt_pk_bf16_f32 v118, v108, v109
	v_or_b32_e32 v108, 16, v152
	v_mad_i64_i32 v[108:109], s[42:43], v108, s3, v[142:143]
	v_cvt_pk_bf16_f32 v119, v110, v111
	global_store_dwordx4 v[150:151], v[116:119], off offset:256
	s_and_b64 vcc, exec, s[4:5]
	s_mov_b32 s10, s22
	v_lshl_add_u64 v[116:117], v[108:109], 0, v[144:145]
	v_cvt_pk_bf16_f32 v108, v120, v121
	v_cvt_pk_bf16_f32 v109, v122, v123
	v_cvt_pk_bf16_f32 v110, v112, v113
	v_cvt_pk_bf16_f32 v111, v114, v115
	global_store_dwordx4 v[116:117], v[108:111], off
	v_cvt_pk_bf16_f32 v100, v100, v101
	v_cvt_pk_bf16_f32 v101, v102, v103
	v_cvt_pk_bf16_f32 v102, v92, v93
	v_or_b32_e32 v92, 32, v152
	v_mad_i64_i32 v[92:93], s[42:43], v92, s3, v[142:143]
	v_cvt_pk_bf16_f32 v103, v94, v95
	global_store_dwordx4 v[116:117], v[100:103], off offset:256
	s_mov_b32 s6, s12
	s_mov_b64 s[44:45], s[40:41]
	v_lshl_add_u64 v[100:101], v[92:93], 0, v[144:145]
	v_cvt_pk_bf16_f32 v92, v104, v105
	v_cvt_pk_bf16_f32 v93, v106, v107
	v_cvt_pk_bf16_f32 v94, v96, v97
	v_cvt_pk_bf16_f32 v95, v98, v99
	global_store_dwordx4 v[100:101], v[92:95], off
	v_cvt_pk_bf16_f32 v84, v84, v85
	v_cvt_pk_bf16_f32 v85, v86, v87
	v_cvt_pk_bf16_f32 v86, v76, v77
	v_or_b32_e32 v76, 48, v152
	v_mad_i64_i32 v[76:77], s[42:43], v76, s3, v[142:143]
	v_cvt_pk_bf16_f32 v87, v78, v79
	global_store_dwordx4 v[100:101], v[84:87], off offset:256
	s_nop 1
	v_lshl_add_u64 v[84:85], v[76:77], 0, v[144:145]
	v_cvt_pk_bf16_f32 v76, v88, v89
	v_cvt_pk_bf16_f32 v77, v90, v91
	v_cvt_pk_bf16_f32 v78, v80, v81
	v_cvt_pk_bf16_f32 v79, v82, v83
	global_store_dwordx4 v[84:85], v[76:79], off
	v_cvt_pk_bf16_f32 v72, v72, v73
	v_cvt_pk_bf16_f32 v73, v74, v75
	v_cvt_pk_bf16_f32 v74, v68, v69
	v_add_u32_e32 v68, 0x80, v152
	v_mad_i64_i32 v[68:69], s[42:43], v68, s3, v[142:143]
	v_lshl_add_u64 v[68:69], v[68:69], 0, v[144:145]
	v_cvt_pk_bf16_f32 v75, v70, v71
	global_store_dwordx4 v[84:85], v[72:75], off offset:256
	v_cvt_pk_bf16_f32 v64, v64, v65
	v_cvt_pk_bf16_f32 v65, v66, v67
	v_cvt_pk_bf16_f32 v66, v60, v61
	v_cvt_pk_bf16_f32 v67, v62, v63
	global_store_dwordx4 v[68:69], v[64:67], off
	v_cvt_pk_bf16_f32 v52, v52, v53
	v_cvt_pk_bf16_f32 v53, v54, v55
	v_cvt_pk_bf16_f32 v54, v44, v45
	v_add_u32_e32 v44, 0x90, v152
	v_mad_i64_i32 v[44:45], s[42:43], v44, s3, v[142:143]
	v_cvt_pk_bf16_f32 v55, v46, v47
	global_store_dwordx4 v[68:69], v[52:55], off offset:256
	s_nop 1
	v_lshl_add_u64 v[52:53], v[44:45], 0, v[144:145]
	v_cvt_pk_bf16_f32 v44, v56, v57
	v_cvt_pk_bf16_f32 v45, v58, v59
	v_cvt_pk_bf16_f32 v46, v48, v49
	v_cvt_pk_bf16_f32 v47, v50, v51
	global_store_dwordx4 v[52:53], v[44:47], off
	v_cvt_pk_bf16_f32 v36, v36, v37
	v_cvt_pk_bf16_f32 v37, v38, v39
	v_cvt_pk_bf16_f32 v38, v28, v29
	v_add_u32_e32 v28, 0xa0, v152
	v_mad_i64_i32 v[28:29], s[42:43], v28, s3, v[142:143]
	v_cvt_pk_bf16_f32 v39, v30, v31
	global_store_dwordx4 v[52:53], v[36:39], off offset:256
	s_nop 1
	v_lshl_add_u64 v[36:37], v[28:29], 0, v[144:145]
	v_cvt_pk_bf16_f32 v28, v40, v41
	v_cvt_pk_bf16_f32 v29, v42, v43
	v_cvt_pk_bf16_f32 v30, v32, v33
	v_cvt_pk_bf16_f32 v31, v34, v35
	global_store_dwordx4 v[36:37], v[28:31], off
	v_cvt_pk_bf16_f32 v20, v20, v21
	v_cvt_pk_bf16_f32 v21, v22, v23
	v_cvt_pk_bf16_f32 v22, v12, v13
	v_add_u32_e32 v12, 0xb0, v152
	v_mad_i64_i32 v[12:13], s[42:43], v12, s3, v[142:143]
	v_cvt_pk_bf16_f32 v23, v14, v15
	global_store_dwordx4 v[36:37], v[20:23], off offset:256
	s_mov_b64 s[42:43], s[38:39]
	s_nop 0
	v_lshl_add_u64 v[20:21], v[12:13], 0, v[144:145]
	v_cvt_pk_bf16_f32 v12, v24, v25
	v_cvt_pk_bf16_f32 v13, v26, v27
	v_cvt_pk_bf16_f32 v14, v16, v17
	v_cvt_pk_bf16_f32 v15, v18, v19
	global_store_dwordx4 v[20:21], v[12:15], off
	v_cvt_pk_bf16_f32 v8, v8, v9
	v_cvt_pk_bf16_f32 v9, v10, v11
	v_cvt_pk_bf16_f32 v10, v4, v5
	v_cvt_pk_bf16_f32 v11, v6, v7
	global_store_dwordx4 v[20:21], v[8:11], off offset:256
	s_cbranch_vccz .LBB0_507
	s_waitcnt vmcnt(0)
	s_cmpk_gt_u32 s8, 0xff
	s_cbranch_scc1 .LBB0_518
	s_barrier

; #define PG8_STAGE(bufoff, gbase, voff) do { _Pragma("unroll") for (int _i = 0; _i < 2; ++_i) \
;         __builtin_amdgcn_global_load_lds((const unsigned*)((const char*)(gbase) + (voff)[_i]), (PG8_LAS unsigned*)(lds + (bufoff) + ldsw + _i * 8192), 16, 0, 0); } while (0)
; #define PG8_LDA(dst, b, h) do { _Pragma("unroll") for (int m = 0; m < 4; ++m) _Pragma("unroll") for (int k = 0; k < 2; ++k) dst[m][k] = *(const PG8_LAS bf16x8*)(lds + PG8_SA(b, h) + aoff + m * 2048 + k * 1024); } while (0)
; #define PG8_LDB(dst, b, h) do { _Pragma("unroll") for (int n = 0; n < 2; ++n) _Pragma("unroll") for (int k = 0; k < 2; ++k) dst[n][k] = *(const PG8_LAS bf16x8*)(lds + PG8_SB(b, h) + boff + n * 2048 + k * 1024); } while (0)
; #define PG8_MMA(ai, bj, At, Bt) do { __builtin_amdgcn_s_setprio(1); _Pragma("unroll") for (int m = 0; m < 4; ++m) _Pragma("unroll") for (int n = 0; n < 2; ++n) _Pragma("unroll") for (int k = 0; k < 2; ++k) \
;         acc[ai][bj][m][n] = __builtin_amdgcn_mfma_f32_16x16x32_bf16(Bt[n][k], At[m][k], acc[ai][bj][m][n], 0, 0, 0); __builtin_amdgcn_s_setprio(0); } while (0)
; #define PG8_WAIT_V(n) asm volatile("s_waitcnt vmcnt(" #n ")" ::: "memory")
; #define PG8_WAIT_L(n) asm volatile("s_waitcnt lgkmcnt(" #n ")" ::: "memory")
; template <class Epi, class Sched, bool ALIGN_EPI = true>
; __device__ __forceinline__ void gemm_phase(PG8_LAS unsigned char* lds, const Gemm g, const Sched& S, const Epi& E, const int tid) {
;     ...
;         for (int t = 0; t < nt; t += 2) {
;             const bool last = (t == nt - 2);
;             const char* a1 = cA + (size_t)(t + 1) * kstep;
;             const char* a2 = last ? nA : cA + (size_t)(t + 2) * kstep; const char* b2 = last ? nB : cB + (size_t)(t + 2) * kstep;
;             const char* a3 = a2 + kstep; const char* b3 = b2 + kstep;
;             if (last && has_next) S.a_ready(nxt);
;             PG8_LDB(B0, 0, 0); PG8_LDB(B1, 0, 1); PG8_SCHED; PG8_LDA(At, 0, 0); PG8_STAGE(PG8_SA(1, 1), a1 + hstepA, voffA);
;             PG8_WAIT_V(8); PG8_WAIT_L(0); PG8_BAR; PG8_MMA(0, 0, At, B0); PG8_MMA(0, 1, At, B1); PG8_BAR; PG8_SCHED;
;             PG8_LDA(At, 0, 1); PG8_STAGE(PG8_SB(0, 0), b2, voffB); PG8_STAGE(PG8_SB(0, 1), b2 + hstepB, voffB); PG8_STAGE(PG8_SA(0, 0), a2, voffA);
;             PG8_WAIT_V(8); PG8_WAIT_L(0); PG8_BAR; PG8_MMA(1, 0, At, B0); PG8_MMA(1, 1, At, B1); PG8_BAR; PG8_SCHED;
.LBB0_1087:
	s_add_i32 s45, s22, 2
	s_add_u32 s15, s12, 0xfff80080
	s_addc_u32 s16, s13, -1
	s_add_i32 s17, 0, 0x10000
	s_cmp_eq_u32 s1, s22
	s_cselect_b32 s55, s51, s16
	s_cselect_b32 s54, s50, s15
	s_cselect_b32 s23, s53, s21
	s_cselect_b32 s22, s52, s20
	s_add_i32 s15, 0, 0x14000
	v_add_u32_e32 v72, s17, v251
	v_add_u32_e32 v128, s15, v251
	ds_read_b128 v[56:59], v72
	ds_read_b128 v[64:67], v72 offset:1024
	ds_read_b128 v[68:71], v72 offset:2048
	ds_read_b128 v[72:75], v72 offset:3072
	ds_read_b128 v[92:95], v128
	ds_read_b128 v[104:107], v128 offset:1024
	ds_read_b128 v[116:119], v128 offset:2048
	ds_read_b128 v[128:131], v128 offset:3072
	v_lshl_add_u64 v[196:197], s[12:13], 0, v[216:217]
	s_add_i32 m0, s11, 0xc000
	ds_read_b128 v[140:143], v252
	ds_read_b128 v[152:155], v252 offset:1024
	ds_read_b128 v[156:159], v252 offset:2048
	ds_read_b128 v[160:163], v252 offset:3072
	ds_read_b128 v[172:175], v252 offset:4096
	ds_read_b128 v[184:187], v252 offset:5120
	ds_read_b128 v[188:191], v252 offset:6144
	ds_read_b128 v[192:195], v252 offset:7168
	global_load_lds_dwordx4 v[196:197], off
	v_lshl_add_u64 v[196:197], s[12:13], 0, v[218:219]
	s_add_i32 m0, s11, 0xe000
	s_nop 0
	global_load_lds_dwordx4 v[196:197], off
	s_waitcnt vmcnt(8)
	s_waitcnt lgkmcnt(0)
	s_barrier
	s_waitcnt lgkmcnt(0)
	v_mfma_f32_16x16x32_bf16 v[180:183], v[56:59], v[140:143], v[180:183]
	v_mfma_f32_16x16x32_bf16 v[180:183], v[64:67], v[152:155], v[180:183]
	v_mfma_f32_16x16x32_bf16 v[176:179], v[68:71], v[140:143], v[176:179]
	v_mfma_f32_16x16x32_bf16 v[176:179], v[72:75], v[152:155], v[176:179]
	v_mfma_f32_16x16x32_bf16 v[148:151], v[56:59], v[156:159], v[148:151]
	v_mfma_f32_16x16x32_bf16 v[148:151], v[64:67], v[160:163], v[148:151]
	v_mfma_f32_16x16x32_bf16 v[144:147], v[68:71], v[156:159], v[144:147]
	v_mfma_f32_16x16x32_bf16 v[144:147], v[72:75], v[160:163], v[144:147]
	v_mfma_f32_16x16x32_bf16 v[124:127], v[56:59], v[172:175], v[124:127]
	v_mfma_f32_16x16x32_bf16 v[124:127], v[64:67], v[184:187], v[124:127]
	v_mfma_f32_16x16x32_bf16 v[120:123], v[68:71], v[172:175], v[120:123]
	v_mfma_f32_16x16x32_bf16 v[120:123], v[72:75], v[184:187], v[120:123]
	v_mfma_f32_16x16x32_bf16 v[100:103], v[56:59], v[188:191], v[100:103]
	v_mfma_f32_16x16x32_bf16 v[100:103], v[64:67], v[192:195], v[100:103]
	v_mfma_f32_16x16x32_bf16 v[96:99], v[68:71], v[188:191], v[96:99]
	v_mfma_f32_16x16x32_bf16 v[96:99], v[72:75], v[192:195], v[96:99]
	v_mfma_f32_16x16x32_bf16 v[168:171], v[92:95], v[140:143], v[168:171]
	v_mfma_f32_16x16x32_bf16 v[136:139], v[92:95], v[156:159], v[136:139]
	v_mfma_f32_16x16x32_bf16 v[132:135], v[116:119], v[156:159], v[132:135]
	v_mfma_f32_16x16x32_bf16 v[112:115], v[92:95], v[172:175], v[112:115]
	v_mfma_f32_16x16x32_bf16 v[108:111], v[116:119], v[172:175], v[108:111]
	v_mfma_f32_16x16x32_bf16 v[88:91], v[92:95], v[188:191], v[88:91]
	v_mfma_f32_16x16x32_bf16 v[84:87], v[116:119], v[188:191], v[84:87]
	v_mfma_f32_16x16x32_bf16 v[168:171], v[104:107], v[152:155], v[168:171]
	v_mfma_f32_16x16x32_bf16 v[140:143], v[116:119], v[140:143], v[164:167]
	v_mfma_f32_16x16x32_bf16 v[136:139], v[104:107], v[160:163], v[136:139]
	v_mfma_f32_16x16x32_bf16 v[132:135], v[128:131], v[160:163], v[132:135]
	v_mfma_f32_16x16x32_bf16 v[112:115], v[104:107], v[184:187], v[112:115]
	v_mfma_f32_16x16x32_bf16 v[108:111], v[128:131], v[184:187], v[108:111]
	v_mfma_f32_16x16x32_bf16 v[88:91], v[104:107], v[192:195], v[88:91]
	v_mfma_f32_16x16x32_bf16 v[84:87], v[128:131], v[192:195], v[84:87]
	v_mfma_f32_16x16x32_bf16 v[140:143], v[128:131], v[152:155], v[140:143]
	s_barrier
	s_add_i32 s16, s17, s60
	v_lshl_add_u64 v[200:201], s[22:23], 0, v[2:3]
	s_mov_b32 m0, s16
	ds_read_b128 v[152:155], v252 offset:16384
	ds_read_b128 v[156:159], v252 offset:17408
	ds_read_b128 v[160:163], v252 offset:18432
	ds_read_b128 v[164:167], v252 offset:19456
	ds_read_b128 v[172:175], v252 offset:20480
	ds_read_b128 v[184:187], v252 offset:21504
	ds_read_b128 v[188:191], v252 offset:22528
	ds_read_b128 v[192:195], v252 offset:23552
	global_load_lds_dwordx4 v[200:201], off
	s_add_i32 m0, s16, 0x2000
	s_add_u32 s72, s22, 0x80000
	v_lshl_add_u64 v[202:203], s[22:23], 0, v[214:215]
	s_addc_u32 s73, s23, 0
	s_add_i32 s15, s15, s60
	global_load_lds_dwordx4 v[202:203], off
	v_lshl_add_u64 v[196:197], s[72:73], 0, v[2:3]
	s_mov_b32 m0, s15
	v_lshl_add_u64 v[204:205], s[54:55], 0, v[210:211]
	global_load_lds_dwordx4 v[196:197], off
	v_lshl_add_u64 v[196:197], s[72:73], 0, v[214:215]
	s_add_i32 m0, s15, 0x2000
	v_lshl_add_u64 v[206:207], s[54:55], 0, v[212:213]
	global_load_lds_dwordx4 v[196:197], off
	s_mov_b32 m0, s11
	s_nop 0
	global_load_lds_dwordx4 v[204:205], off
	s_mov_b32 m0, s61
	s_nop 0
	global_load_lds_dwordx4 v[206:207], off
	s_waitcnt vmcnt(8)
	s_waitcnt lgkmcnt(0)
	s_barrier
; #define PG8_STAGE(bufoff, gbase, voff) do { _Pragma("unroll") for (int _i = 0; _i < 2; ++_i) \
;         __builtin_amdgcn_global_load_lds((const unsigned*)((const char*)(gbase) + (voff)[_i]), (PG8_LAS unsigned*)(lds + (bufoff) + ldsw + _i * 8192), 16, 0, 0); } while (0)
; #define PG8_LDA(dst, b, h) do { _Pragma("unroll") for (int m = 0; m < 4; ++m) _Pragma("unroll") for (int k = 0; k < 2; ++k) dst[m][k] = *(const PG8_LAS bf16x8*)(lds + PG8_SA(b, h) + aoff + m * 2048 + k * 1024); } while (0)
; #define PG8_LDB(dst, b, h) do { _Pragma("unroll") for (int n = 0; n < 2; ++n) _Pragma("unroll") for (int k = 0; k < 2; ++k) dst[n][k] = *(const PG8_LAS bf16x8*)(lds + PG8_SB(b, h) + boff + n * 2048 + k * 1024); } while (0)
; #define PG8_MMA(ai, bj, At, Bt) do { __builtin_amdgcn_s_setprio(1); _Pragma("unroll") for (int m = 0; m < 4; ++m) _Pragma("unroll") for (int n = 0; n < 2; ++n) _Pragma("unroll") for (int k = 0; k < 2; ++k) \
;         acc[ai][bj][m][n] = __builtin_amdgcn_mfma_f32_16x16x32_bf16(Bt[n][k], At[m][k], acc[ai][bj][m][n], 0, 0, 0); __builtin_amdgcn_s_setprio(0); } while (0)
; #define PG8_WAIT_V(n) asm volatile("s_waitcnt vmcnt(" #n ")" ::: "memory")
; #define PG8_WAIT_L(n) asm volatile("s_waitcnt lgkmcnt(" #n ")" ::: "memory")
; #define PG8_BAR __builtin_amdgcn_s_barrier()
; #define PG8_SCHED __builtin_amdgcn_sched_barrier(0)
; template <class Epi, class Sched, bool ALIGN_EPI = true>
; __device__ __forceinline__ void gemm_phase(PG8_LAS unsigned char* lds, const Gemm g, const Sched& S, const Epi& E, const int tid) {
;     ...
;             PG8_WAIT_V(8); PG8_WAIT_L(0); PG8_BAR; PG8_MMA(1, 0, At, B0); PG8_MMA(1, 1, At, B1); PG8_BAR; PG8_SCHED;
;             PG8_LDB(B0, 1, 0); PG8_LDB(B1, 1, 1); PG8_SCHED; PG8_LDA(At, 1, 0); PG8_STAGE(PG8_SA(0, 1), a2 + hstepA, voffA);
;             PG8_WAIT_V(8); PG8_WAIT_L(0); PG8_BAR; PG8_MMA(0, 0, At, B0); PG8_MMA(0, 1, At, B1); PG8_BAR; PG8_SCHED;
	s_waitcnt lgkmcnt(0)
	v_mfma_f32_16x16x32_bf16 v[80:83], v[56:59], v[152:155], v[80:83]
	v_mfma_f32_16x16x32_bf16 v[80:83], v[64:67], v[156:159], v[80:83]
	v_mfma_f32_16x16x32_bf16 v[76:79], v[68:71], v[152:155], v[76:79]
	v_mfma_f32_16x16x32_bf16 v[76:79], v[72:75], v[156:159], v[76:79]
	v_mfma_f32_16x16x32_bf16 v[48:51], v[56:59], v[160:163], v[48:51]
	v_mfma_f32_16x16x32_bf16 v[48:51], v[64:67], v[164:167], v[48:51]
	v_mfma_f32_16x16x32_bf16 v[44:47], v[68:71], v[160:163], v[44:47]
	v_mfma_f32_16x16x32_bf16 v[44:47], v[72:75], v[164:167], v[44:47]
	v_mfma_f32_16x16x32_bf16 v[32:35], v[56:59], v[172:175], v[32:35]
	v_mfma_f32_16x16x32_bf16 v[32:35], v[64:67], v[184:187], v[32:35]
	v_mfma_f32_16x16x32_bf16 v[28:31], v[68:71], v[172:175], v[28:31]
	v_mfma_f32_16x16x32_bf16 v[28:31], v[72:75], v[184:187], v[28:31]
	v_mfma_f32_16x16x32_bf16 v[16:19], v[56:59], v[188:191], v[16:19]
	v_mfma_f32_16x16x32_bf16 v[16:19], v[64:67], v[192:195], v[16:19]
	v_mfma_f32_16x16x32_bf16 v[12:15], v[68:71], v[188:191], v[12:15]
	v_mfma_f32_16x16x32_bf16 v[12:15], v[72:75], v[192:195], v[12:15]
	v_mfma_f32_16x16x32_bf16 v[52:55], v[116:119], v[152:155], v[52:55]
	v_mfma_f32_16x16x32_bf16 v[40:43], v[92:95], v[160:163], v[40:43]
	v_mfma_f32_16x16x32_bf16 v[36:39], v[116:119], v[160:163], v[36:39]
	v_mfma_f32_16x16x32_bf16 v[24:27], v[92:95], v[172:175], v[24:27]
	v_mfma_f32_16x16x32_bf16 v[20:23], v[116:119], v[172:175], v[20:23]
	v_mfma_f32_16x16x32_bf16 v[8:11], v[92:95], v[188:191], v[8:11]
	v_mfma_f32_16x16x32_bf16 v[4:7], v[116:119], v[188:191], v[4:7]
	v_mfma_f32_16x16x32_bf16 v[56:59], v[92:95], v[152:155], v[60:63]
	v_mfma_f32_16x16x32_bf16 v[52:55], v[128:131], v[156:159], v[52:55]
	v_mfma_f32_16x16x32_bf16 v[40:43], v[104:107], v[164:167], v[40:43]
	v_mfma_f32_16x16x32_bf16 v[36:39], v[128:131], v[164:167], v[36:39]
	v_mfma_f32_16x16x32_bf16 v[24:27], v[104:107], v[184:187], v[24:27]
	v_mfma_f32_16x16x32_bf16 v[20:23], v[128:131], v[184:187], v[20:23]
	v_mfma_f32_16x16x32_bf16 v[8:11], v[104:107], v[192:195], v[8:11]
	v_mfma_f32_16x16x32_bf16 v[4:7], v[128:131], v[192:195], v[4:7]
	v_mfma_f32_16x16x32_bf16 v[56:59], v[104:107], v[156:159], v[56:59]
	s_barrier
	s_add_i32 s15, 0, 0x18000
	s_add_i32 s16, 0, 0x1c000
	v_add_u32_e32 v72, s15, v251
	v_add_u32_e32 v128, s16, v251
	ds_read_b128 v[60:63], v72
	ds_read_b128 v[64:67], v72 offset:1024
	ds_read_b128 v[68:71], v72 offset:2048
	ds_read_b128 v[72:75], v72 offset:3072
	ds_read_b128 v[92:95], v128
	ds_read_b128 v[104:107], v128 offset:1024
	ds_read_b128 v[116:119], v128 offset:2048
	ds_read_b128 v[128:131], v128 offset:3072
	s_add_u32 s54, s54, 0x80000
	s_addc_u32 s55, s55, 0
	s_mov_b32 m0, s62
	v_lshl_add_u64 v[164:165], s[54:55], 0, v[210:211]
	ds_read_b128 v[152:155], v252 offset:32768
	ds_read_b128 v[156:159], v252 offset:33792
	ds_read_b128 v[160:163], v252 offset:34816
	ds_read_b128 v[172:175], v252 offset:35840
	ds_read_b128 v[184:187], v252 offset:36864
	ds_read_b128 v[188:191], v252 offset:37888
	ds_read_b128 v[192:195], v252 offset:38912
	ds_read_b128 v[196:199], v252 offset:39936
	global_load_lds_dwordx4 v[164:165], off
	v_lshl_add_u64 v[164:165], s[54:55], 0, v[212:213]
	s_mov_b32 m0, s63
	s_nop 0
	global_load_lds_dwordx4 v[164:165], off
	s_waitcnt vmcnt(8)
	s_waitcnt lgkmcnt(0)
	s_barrier
	s_waitcnt lgkmcnt(0)
	v_mfma_f32_16x16x32_bf16 v[164:167], v[60:63], v[152:155], v[180:183]
	v_mfma_f32_16x16x32_bf16 v[180:183], v[64:67], v[156:159], v[164:167]
	v_mfma_f32_16x16x32_bf16 v[164:167], v[68:71], v[152:155], v[176:179]
	v_mfma_f32_16x16x32_bf16 v[148:151], v[60:63], v[160:163], v[148:151]
	v_mfma_f32_16x16x32_bf16 v[144:147], v[68:71], v[160:163], v[144:147]
	v_mfma_f32_16x16x32_bf16 v[124:127], v[60:63], v[184:187], v[124:127]
	v_mfma_f32_16x16x32_bf16 v[120:123], v[68:71], v[184:187], v[120:123]
	v_mfma_f32_16x16x32_bf16 v[100:103], v[60:63], v[192:195], v[100:103]
	v_mfma_f32_16x16x32_bf16 v[96:99], v[68:71], v[192:195], v[96:99]
	v_mfma_f32_16x16x32_bf16 v[176:179], v[72:75], v[156:159], v[164:167]
	v_mfma_f32_16x16x32_bf16 v[148:151], v[64:67], v[172:175], v[148:151]
	v_mfma_f32_16x16x32_bf16 v[144:147], v[72:75], v[172:175], v[144:147]
	v_mfma_f32_16x16x32_bf16 v[124:127], v[64:67], v[188:191], v[124:127]
	v_mfma_f32_16x16x32_bf16 v[120:123], v[72:75], v[188:191], v[120:123]
	v_mfma_f32_16x16x32_bf16 v[100:103], v[64:67], v[196:199], v[100:103]
	v_mfma_f32_16x16x32_bf16 v[96:99], v[72:75], v[196:199], v[96:99]
	v_mfma_f32_16x16x32_bf16 v[164:167], v[92:95], v[152:155], v[168:171]
	v_mfma_f32_16x16x32_bf16 v[140:143], v[116:119], v[152:155], v[140:143]
	v_mfma_f32_16x16x32_bf16 v[136:139], v[92:95], v[160:163], v[136:139]
	v_mfma_f32_16x16x32_bf16 v[132:135], v[116:119], v[160:163], v[132:135]
	v_mfma_f32_16x16x32_bf16 v[112:115], v[92:95], v[184:187], v[112:115]
	v_mfma_f32_16x16x32_bf16 v[108:111], v[116:119], v[184:187], v[108:111]
	v_mfma_f32_16x16x32_bf16 v[88:91], v[92:95], v[192:195], v[88:91]
	v_mfma_f32_16x16x32_bf16 v[84:87], v[116:119], v[192:195], v[84:87]
	v_mfma_f32_16x16x32_bf16 v[168:171], v[104:107], v[156:159], v[164:167]
	v_mfma_f32_16x16x32_bf16 v[164:167], v[128:131], v[156:159], v[140:143]
	v_mfma_f32_16x16x32_bf16 v[136:139], v[104:107], v[172:175], v[136:139]
	v_mfma_f32_16x16x32_bf16 v[132:135], v[128:131], v[172:175], v[132:135]
	v_mfma_f32_16x16x32_bf16 v[112:115], v[104:107], v[188:191], v[112:115]
	v_mfma_f32_16x16x32_bf16 v[108:111], v[128:131], v[188:191], v[108:111]
	v_mfma_f32_16x16x32_bf16 v[88:91], v[104:107], v[196:199], v[88:91]
	v_mfma_f32_16x16x32_bf16 v[84:87], v[128:131], v[196:199], v[84:87]
	s_barrier
; #define PG8_STAGE(bufoff, gbase, voff) do { _Pragma("unroll") for (int _i = 0; _i < 2; ++_i) \
;         __builtin_amdgcn_global_load_lds((const unsigned*)((const char*)(gbase) + (voff)[_i]), (PG8_LAS unsigned*)(lds + (bufoff) + ldsw + _i * 8192), 16, 0, 0); } while (0)
; #define PG8_LDA(dst, b, h) do { _Pragma("unroll") for (int m = 0; m < 4; ++m) _Pragma("unroll") for (int k = 0; k < 2; ++k) dst[m][k] = *(const PG8_LAS bf16x8*)(lds + PG8_SA(b, h) + aoff + m * 2048 + k * 1024); } while (0)
; #define PG8_MMA(ai, bj, At, Bt) do { __builtin_amdgcn_s_setprio(1); _Pragma("unroll") for (int m = 0; m < 4; ++m) _Pragma("unroll") for (int n = 0; n < 2; ++n) _Pragma("unroll") for (int k = 0; k < 2; ++k) \
;         acc[ai][bj][m][n] = __builtin_amdgcn_mfma_f32_16x16x32_bf16(Bt[n][k], At[m][k], acc[ai][bj][m][n], 0, 0, 0); __builtin_amdgcn_s_setprio(0); } while (0)
; #define PG8_WAIT_V(n) asm volatile("s_waitcnt vmcnt(" #n ")" ::: "memory")
; #define PG8_WAIT_L(n) asm volatile("s_waitcnt lgkmcnt(" #n ")" ::: "memory")
; #define PG8_BAR __builtin_amdgcn_s_barrier()
; #define PG8_SCHED __builtin_amdgcn_sched_barrier(0)
; template <class Epi, class Sched, bool ALIGN_EPI = true>
; __device__ __forceinline__ void gemm_phase(PG8_LAS unsigned char* lds, const Gemm g, const Sched& S, const Epi& E, const int tid) {
;     ...
;             PG8_LDA(At, 1, 1); PG8_STAGE(PG8_SB(1, 0), b3, voffB); PG8_STAGE(PG8_SB(1, 1), b3 + hstepB, voffB); PG8_STAGE(PG8_SA(1, 0), a3, voffA);
;             PG8_WAIT_V(8); PG8_WAIT_L(0); PG8_BAR; PG8_MMA(1, 0, At, B0); PG8_MMA(1, 1, At, B1); PG8_BAR; PG8_SCHED;
;         }
;         if constexpr (ALIGN_EPI) { if (wr == 0) PG8_BAR; }
	s_add_i32 s15, s15, s60
	v_lshl_add_u64 v[196:197], v[200:201], 0, s[36:37]
	s_mov_b32 m0, s15
	ds_read_b128 v[140:143], v252 offset:49152
	ds_read_b128 v[152:155], v252 offset:50176
	ds_read_b128 v[156:159], v252 offset:51200
	ds_read_b128 v[160:163], v252 offset:52224
	ds_read_b128 v[172:175], v252 offset:53248
	ds_read_b128 v[184:187], v252 offset:54272
	ds_read_b128 v[188:191], v252 offset:55296
	ds_read_b128 v[192:195], v252 offset:56320
	global_load_lds_dwordx4 v[196:197], off
	s_add_i32 m0, s15, 0x2000
	s_add_u32 s22, s22, 0x80080
	v_lshl_add_u64 v[196:197], v[202:203], 0, s[36:37]
	s_addc_u32 s23, s23, 0
	s_add_i32 s15, s16, s60
	global_load_lds_dwordx4 v[196:197], off
	v_lshl_add_u64 v[196:197], s[22:23], 0, v[2:3]
	s_mov_b32 m0, s15
	s_nop 0
	global_load_lds_dwordx4 v[196:197], off
	v_lshl_add_u64 v[196:197], s[22:23], 0, v[214:215]
	s_add_i32 m0, s15, 0x2000
	s_nop 0
	global_load_lds_dwordx4 v[196:197], off
	v_lshl_add_u64 v[196:197], v[204:205], 0, s[36:37]
	s_mov_b32 m0, s68
	s_nop 0
	global_load_lds_dwordx4 v[196:197], off
	v_lshl_add_u64 v[196:197], v[206:207], 0, s[36:37]
	s_mov_b32 m0, s69
	s_nop 0
	global_load_lds_dwordx4 v[196:197], off
	s_waitcnt vmcnt(8)
	s_waitcnt lgkmcnt(0)
	s_barrier
	s_waitcnt lgkmcnt(0)
	v_mfma_f32_16x16x32_bf16 v[80:83], v[60:63], v[140:143], v[80:83]
	v_mfma_f32_16x16x32_bf16 v[80:83], v[64:67], v[152:155], v[80:83]
	v_mfma_f32_16x16x32_bf16 v[76:79], v[68:71], v[140:143], v[76:79]
	v_mfma_f32_16x16x32_bf16 v[76:79], v[72:75], v[152:155], v[76:79]
	v_mfma_f32_16x16x32_bf16 v[48:51], v[60:63], v[156:159], v[48:51]
	v_mfma_f32_16x16x32_bf16 v[48:51], v[64:67], v[160:163], v[48:51]
	v_mfma_f32_16x16x32_bf16 v[44:47], v[68:71], v[156:159], v[44:47]
	v_mfma_f32_16x16x32_bf16 v[44:47], v[72:75], v[160:163], v[44:47]
	v_mfma_f32_16x16x32_bf16 v[32:35], v[60:63], v[172:175], v[32:35]
	v_mfma_f32_16x16x32_bf16 v[32:35], v[64:67], v[184:187], v[32:35]
	v_mfma_f32_16x16x32_bf16 v[28:31], v[68:71], v[172:175], v[28:31]
	v_mfma_f32_16x16x32_bf16 v[28:31], v[72:75], v[184:187], v[28:31]
	v_mfma_f32_16x16x32_bf16 v[16:19], v[60:63], v[188:191], v[16:19]
	v_mfma_f32_16x16x32_bf16 v[16:19], v[64:67], v[192:195], v[16:19]
	v_mfma_f32_16x16x32_bf16 v[12:15], v[68:71], v[188:191], v[12:15]
	v_mfma_f32_16x16x32_bf16 v[12:15], v[72:75], v[192:195], v[12:15]
	v_mfma_f32_16x16x32_bf16 v[56:59], v[92:95], v[140:143], v[56:59]
	v_mfma_f32_16x16x32_bf16 v[52:55], v[116:119], v[140:143], v[52:55]
	v_mfma_f32_16x16x32_bf16 v[40:43], v[92:95], v[156:159], v[40:43]
	v_mfma_f32_16x16x32_bf16 v[36:39], v[116:119], v[156:159], v[36:39]
	v_mfma_f32_16x16x32_bf16 v[24:27], v[92:95], v[172:175], v[24:27]
	v_mfma_f32_16x16x32_bf16 v[20:23], v[116:119], v[172:175], v[20:23]
	v_mfma_f32_16x16x32_bf16 v[8:11], v[92:95], v[188:191], v[8:11]
	v_mfma_f32_16x16x32_bf16 v[4:7], v[116:119], v[188:191], v[4:7]
	v_mfma_f32_16x16x32_bf16 v[60:63], v[104:107], v[152:155], v[56:59]
	v_mfma_f32_16x16x32_bf16 v[52:55], v[128:131], v[152:155], v[52:55]
	v_mfma_f32_16x16x32_bf16 v[40:43], v[104:107], v[160:163], v[40:43]
	v_mfma_f32_16x16x32_bf16 v[36:39], v[128:131], v[160:163], v[36:39]
	v_mfma_f32_16x16x32_bf16 v[24:27], v[104:107], v[184:187], v[24:27]
	v_mfma_f32_16x16x32_bf16 v[20:23], v[128:131], v[184:187], v[20:23]
	v_mfma_f32_16x16x32_bf16 v[8:11], v[104:107], v[192:195], v[8:11]
	v_mfma_f32_16x16x32_bf16 v[4:7], v[128:131], v[192:195], v[4:7]
	s_barrier
	s_add_u32 s12, s12, 0x100
	s_addc_u32 s13, s13, 0
	s_add_u32 s20, s20, 0x100
	s_addc_u32 s21, s21, 0
	s_cmp_ge_i32 s45, s9
	s_mov_b32 s22, s45
	s_cbranch_scc0 .LBB0_1087
	s_and_b64 vcc, exec, s[42:43]
	s_cbranch_vccz .LBB0_1090
	s_barrier

; #define PG8_STAGE(bufoff, gbase, voff) do { _Pragma("unroll") for (int _i = 0; _i < 2; ++_i) \
;         __builtin_amdgcn_global_load_lds((const unsigned*)((const char*)(gbase) + (voff)[_i]), (PG8_LAS unsigned*)(lds + (bufoff) + ldsw + _i * 8192), 16, 0, 0); } while (0)
; #define PG8_LDA(dst, b, h) do { _Pragma("unroll") for (int m = 0; m < 4; ++m) _Pragma("unroll") for (int k = 0; k < 2; ++k) dst[m][k] = *(const PG8_LAS bf16x8*)(lds + PG8_SA(b, h) + aoff + m * 2048 + k * 1024); } while (0)
; #define PG8_LDB(dst, b, h) do { _Pragma("unroll") for (int n = 0; n < 2; ++n) _Pragma("unroll") for (int k = 0; k < 2; ++k) dst[n][k] = *(const PG8_LAS bf16x8*)(lds + PG8_SB(b, h) + boff + n * 2048 + k * 1024); } while (0)
; #define PG8_MMA(ai, bj, At, Bt) do { __builtin_amdgcn_s_setprio(1); _Pragma("unroll") for (int m = 0; m < 4; ++m) _Pragma("unroll") for (int n = 0; n < 2; ++n) _Pragma("unroll") for (int k = 0; k < 2; ++k) \
;         acc[ai][bj][m][n] = __builtin_amdgcn_mfma_f32_16x16x32_bf16(Bt[n][k], At[m][k], acc[ai][bj][m][n], 0, 0, 0); __builtin_amdgcn_s_setprio(0); } while (0)
; #define PG8_WAIT_V(n) asm volatile("s_waitcnt vmcnt(" #n ")" ::: "memory")
; #define PG8_WAIT_L(n) asm volatile("s_waitcnt lgkmcnt(" #n ")" ::: "memory")
; template <class Epi, class Sched, bool ALIGN_EPI = true>
; __device__ __forceinline__ void gemm_phase(PG8_LAS unsigned char* lds, const Gemm g, const Sched& S, const Epi& E, const int tid) {
;     ...
;         for (int t = 0; t < nt; t += 2) {
;             const bool last = (t == nt - 2);
;             const char* a1 = cA + (size_t)(t + 1) * kstep;
;             const char* a2 = last ? nA : cA + (size_t)(t + 2) * kstep; const char* b2 = last ? nB : cB + (size_t)(t + 2) * kstep;
;             const char* a3 = a2 + kstep; const char* b3 = b2 + kstep;
;             if (last && has_next) S.a_ready(nxt);
;             PG8_LDB(B0, 0, 0); PG8_LDB(B1, 0, 1); PG8_SCHED; PG8_LDA(At, 0, 0); PG8_STAGE(PG8_SA(1, 1), a1 + hstepA, voffA);
;             PG8_WAIT_V(8); PG8_WAIT_L(0); PG8_BAR; PG8_MMA(0, 0, At, B0); PG8_MMA(0, 1, At, B1); PG8_BAR; PG8_SCHED;
;             PG8_LDA(At, 0, 1); PG8_STAGE(PG8_SB(0, 0), b2, voffB); PG8_STAGE(PG8_SB(0, 1), b2 + hstepB, voffB); PG8_STAGE(PG8_SA(0, 0), a2, voffA);
;             PG8_WAIT_V(8); PG8_WAIT_L(0); PG8_BAR; PG8_MMA(1, 0, At, B0); PG8_MMA(1, 1, At, B1); PG8_BAR; PG8_SCHED;
.LBB0_1238:
	s_add_u32 s15, s74, 0xfff80080
	s_addc_u32 s16, s75, -1
	s_add_i32 s17, 0, 0x10000
	s_cmp_eq_u32 s21, 28
	s_cselect_b32 s79, s8, s16
	s_cselect_b32 s78, s11, s15
	s_cselect_b32 s77, s13, s20
	s_cselect_b32 s76, s18, s19
	s_add_i32 s15, 0, 0x14000
	v_add_u32_e32 v88, s17, v193
	v_add_u32_e32 v104, s15, v193
	ds_read_b128 v[72:75], v88
	ds_read_b128 v[76:79], v88 offset:1024
	ds_read_b128 v[84:87], v88 offset:2048
	ds_read_b128 v[88:91], v88 offset:3072
	ds_read_b128 v[92:95], v104
	ds_read_b128 v[96:99], v104 offset:1024
	ds_read_b128 v[100:103], v104 offset:2048
	ds_read_b128 v[104:107], v104 offset:3072
	v_lshl_add_u64 v[190:191], s[74:75], 0, v[186:187]
	s_add_i32 m0, s86, 0xc000
	ds_read_b128 v[164:167], v200
	ds_read_b128 v[168:171], v200 offset:1024
	ds_read_b128 v[172:175], v200 offset:2048
	ds_read_b128 v[176:179], v200 offset:3072
	ds_read_b128 v[202:205], v200 offset:4096
	ds_read_b128 v[210:213], v200 offset:5120
	ds_read_b128 v[214:217], v200 offset:6144
	ds_read_b128 v[218:221], v200 offset:7168
	global_load_lds_dwordx4 v[190:191], off
	v_lshl_add_u64 v[190:191], s[74:75], 0, v[188:189]
	s_add_i32 m0, s86, 0xe000
	s_nop 0
	global_load_lds_dwordx4 v[190:191], off
	s_waitcnt vmcnt(8)
	s_waitcnt lgkmcnt(0)
	s_barrier
	s_waitcnt lgkmcnt(0)
	v_mfma_f32_16x16x32_bf16 v[160:163], v[72:75], v[164:167], v[160:163]
	v_mfma_f32_16x16x32_bf16 v[160:163], v[76:79], v[168:171], v[160:163]
	v_mfma_f32_16x16x32_bf16 v[156:159], v[84:87], v[164:167], v[156:159]
	v_mfma_f32_16x16x32_bf16 v[156:159], v[88:91], v[168:171], v[156:159]
	v_mfma_f32_16x16x32_bf16 v[144:147], v[72:75], v[172:175], v[144:147]
	v_mfma_f32_16x16x32_bf16 v[144:147], v[76:79], v[176:179], v[144:147]
	v_mfma_f32_16x16x32_bf16 v[140:143], v[84:87], v[172:175], v[140:143]
	v_mfma_f32_16x16x32_bf16 v[140:143], v[88:91], v[176:179], v[140:143]
	v_mfma_f32_16x16x32_bf16 v[128:131], v[72:75], v[202:205], v[128:131]
	v_mfma_f32_16x16x32_bf16 v[128:131], v[76:79], v[210:213], v[128:131]
	v_mfma_f32_16x16x32_bf16 v[124:127], v[84:87], v[202:205], v[124:127]
	v_mfma_f32_16x16x32_bf16 v[124:127], v[88:91], v[210:213], v[124:127]
	v_mfma_f32_16x16x32_bf16 v[80:83], v[72:75], v[214:217], v[80:83]
	v_mfma_f32_16x16x32_bf16 v[80:83], v[76:79], v[218:221], v[80:83]
	v_mfma_f32_16x16x32_bf16 v[68:71], v[84:87], v[214:217], v[68:71]
	v_mfma_f32_16x16x32_bf16 v[68:71], v[88:91], v[218:221], v[68:71]
	v_mfma_f32_16x16x32_bf16 v[152:155], v[92:95], v[164:167], v[152:155]
	v_mfma_f32_16x16x32_bf16 v[152:155], v[96:99], v[168:171], v[152:155]
	v_mfma_f32_16x16x32_bf16 v[148:151], v[100:103], v[164:167], v[148:151]
	v_mfma_f32_16x16x32_bf16 v[148:151], v[104:107], v[168:171], v[148:151]
	v_mfma_f32_16x16x32_bf16 v[136:139], v[92:95], v[172:175], v[136:139]
	v_mfma_f32_16x16x32_bf16 v[136:139], v[96:99], v[176:179], v[136:139]
	v_mfma_f32_16x16x32_bf16 v[132:135], v[100:103], v[172:175], v[132:135]
	v_mfma_f32_16x16x32_bf16 v[132:135], v[104:107], v[176:179], v[132:135]
	v_mfma_f32_16x16x32_bf16 v[120:123], v[92:95], v[202:205], v[120:123]
	v_mfma_f32_16x16x32_bf16 v[120:123], v[96:99], v[210:213], v[120:123]
	v_mfma_f32_16x16x32_bf16 v[116:119], v[100:103], v[202:205], v[116:119]
	v_mfma_f32_16x16x32_bf16 v[116:119], v[104:107], v[210:213], v[116:119]
	v_mfma_f32_16x16x32_bf16 v[112:115], v[92:95], v[214:217], v[112:115]
	v_mfma_f32_16x16x32_bf16 v[112:115], v[96:99], v[218:221], v[112:115]
	v_mfma_f32_16x16x32_bf16 v[108:111], v[100:103], v[214:217], v[108:111]
	v_mfma_f32_16x16x32_bf16 v[108:111], v[104:107], v[218:221], v[108:111]
	s_barrier
	s_add_i32 s16, s17, s85
	v_lshl_add_u64 v[190:191], s[76:77], 0, v[2:3]
	s_mov_b32 m0, s16
	ds_read_b128 v[164:167], v200 offset:16384
	ds_read_b128 v[168:171], v200 offset:17408
	ds_read_b128 v[172:175], v200 offset:18432
	ds_read_b128 v[176:179], v200 offset:19456
	ds_read_b128 v[202:205], v200 offset:20480
	ds_read_b128 v[210:213], v200 offset:21504
	ds_read_b128 v[214:217], v200 offset:22528
	ds_read_b128 v[218:221], v200 offset:23552
	global_load_lds_dwordx4 v[190:191], off
	s_add_i32 m0, s16, 0x2000
	s_add_u32 s96, s76, 0x80000
	v_lshl_add_u64 v[206:207], s[76:77], 0, v[184:185]
	s_addc_u32 s97, s77, 0
	s_add_i32 s15, s15, s85
	global_load_lds_dwordx4 v[206:207], off
	v_lshl_add_u64 v[208:209], s[96:97], 0, v[2:3]
	s_mov_b32 m0, s15
	v_lshl_add_u64 v[222:223], s[78:79], 0, v[182:183]
	global_load_lds_dwordx4 v[208:209], off
	v_lshl_add_u64 v[208:209], s[96:97], 0, v[184:185]
	s_add_i32 m0, s15, 0x2000
	s_nop 0
	global_load_lds_dwordx4 v[208:209], off
	v_lshl_add_u64 v[208:209], s[78:79], 0, v[180:181]
	s_mov_b32 m0, s86
	s_nop 0
	global_load_lds_dwordx4 v[208:209], off
	s_mov_b32 m0, s87
	s_nop 0
	global_load_lds_dwordx4 v[222:223], off
	s_waitcnt vmcnt(8)
	s_waitcnt lgkmcnt(0)
	s_barrier
; #define PG8_STAGE(bufoff, gbase, voff) do { _Pragma("unroll") for (int _i = 0; _i < 2; ++_i) \
;         __builtin_amdgcn_global_load_lds((const unsigned*)((const char*)(gbase) + (voff)[_i]), (PG8_LAS unsigned*)(lds + (bufoff) + ldsw + _i * 8192), 16, 0, 0); } while (0)
; #define PG8_LDA(dst, b, h) do { _Pragma("unroll") for (int m = 0; m < 4; ++m) _Pragma("unroll") for (int k = 0; k < 2; ++k) dst[m][k] = *(const PG8_LAS bf16x8*)(lds + PG8_SA(b, h) + aoff + m * 2048 + k * 1024); } while (0)
; #define PG8_LDB(dst, b, h) do { _Pragma("unroll") for (int n = 0; n < 2; ++n) _Pragma("unroll") for (int k = 0; k < 2; ++k) dst[n][k] = *(const PG8_LAS bf16x8*)(lds + PG8_SB(b, h) + boff + n * 2048 + k * 1024); } while (0)
; #define PG8_MMA(ai, bj, At, Bt) do { __builtin_amdgcn_s_setprio(1); _Pragma("unroll") for (int m = 0; m < 4; ++m) _Pragma("unroll") for (int n = 0; n < 2; ++n) _Pragma("unroll") for (int k = 0; k < 2; ++k) \
;         acc[ai][bj][m][n] = __builtin_amdgcn_mfma_f32_16x16x32_bf16(Bt[n][k], At[m][k], acc[ai][bj][m][n], 0, 0, 0); __builtin_amdgcn_s_setprio(0); } while (0)
; #define PG8_WAIT_V(n) asm volatile("s_waitcnt vmcnt(" #n ")" ::: "memory")
; #define PG8_WAIT_L(n) asm volatile("s_waitcnt lgkmcnt(" #n ")" ::: "memory")
; #define PG8_BAR __builtin_amdgcn_s_barrier()
; #define PG8_SCHED __builtin_amdgcn_sched_barrier(0)
; template <class Epi, class Sched, bool ALIGN_EPI = true>
; __device__ __forceinline__ void gemm_phase(PG8_LAS unsigned char* lds, const Gemm g, const Sched& S, const Epi& E, const int tid) {
;     ...
;             PG8_WAIT_V(8); PG8_WAIT_L(0); PG8_BAR; PG8_MMA(1, 0, At, B0); PG8_MMA(1, 1, At, B1); PG8_BAR; PG8_SCHED;
;             PG8_LDB(B0, 1, 0); PG8_LDB(B1, 1, 1); PG8_SCHED; PG8_LDA(At, 1, 0); PG8_STAGE(PG8_SA(0, 1), a2 + hstepA, voffA);
;             PG8_WAIT_V(8); PG8_WAIT_L(0); PG8_BAR; PG8_MMA(0, 0, At, B0); PG8_MMA(0, 1, At, B1); PG8_BAR; PG8_SCHED;
	s_waitcnt lgkmcnt(0)
	v_mfma_f32_16x16x32_bf16 v[64:67], v[72:75], v[164:167], v[64:67]
	v_mfma_f32_16x16x32_bf16 v[64:67], v[76:79], v[168:171], v[64:67]
	v_mfma_f32_16x16x32_bf16 v[60:63], v[84:87], v[164:167], v[60:63]
	v_mfma_f32_16x16x32_bf16 v[60:63], v[88:91], v[168:171], v[60:63]
	v_mfma_f32_16x16x32_bf16 v[48:51], v[72:75], v[172:175], v[48:51]
	v_mfma_f32_16x16x32_bf16 v[48:51], v[76:79], v[176:179], v[48:51]
	v_mfma_f32_16x16x32_bf16 v[44:47], v[84:87], v[172:175], v[44:47]
	v_mfma_f32_16x16x32_bf16 v[44:47], v[88:91], v[176:179], v[44:47]
	v_mfma_f32_16x16x32_bf16 v[32:35], v[72:75], v[202:205], v[32:35]
	v_mfma_f32_16x16x32_bf16 v[32:35], v[76:79], v[210:213], v[32:35]
	v_mfma_f32_16x16x32_bf16 v[28:31], v[84:87], v[202:205], v[28:31]
	v_mfma_f32_16x16x32_bf16 v[28:31], v[88:91], v[210:213], v[28:31]
	v_mfma_f32_16x16x32_bf16 v[8:11], v[72:75], v[214:217], v[8:11]
	v_mfma_f32_16x16x32_bf16 v[8:11], v[76:79], v[218:221], v[8:11]
	v_mfma_f32_16x16x32_bf16 v[4:7], v[84:87], v[214:217], v[4:7]
	v_mfma_f32_16x16x32_bf16 v[4:7], v[88:91], v[218:221], v[4:7]
	v_mfma_f32_16x16x32_bf16 v[56:59], v[92:95], v[164:167], v[56:59]
	v_mfma_f32_16x16x32_bf16 v[56:59], v[96:99], v[168:171], v[56:59]
	v_mfma_f32_16x16x32_bf16 v[52:55], v[100:103], v[164:167], v[52:55]
	v_mfma_f32_16x16x32_bf16 v[52:55], v[104:107], v[168:171], v[52:55]
	v_mfma_f32_16x16x32_bf16 v[40:43], v[92:95], v[172:175], v[40:43]
	v_mfma_f32_16x16x32_bf16 v[40:43], v[96:99], v[176:179], v[40:43]
	v_mfma_f32_16x16x32_bf16 v[36:39], v[100:103], v[172:175], v[36:39]
	v_mfma_f32_16x16x32_bf16 v[36:39], v[104:107], v[176:179], v[36:39]
	v_mfma_f32_16x16x32_bf16 v[24:27], v[92:95], v[202:205], v[24:27]
	v_mfma_f32_16x16x32_bf16 v[24:27], v[96:99], v[210:213], v[24:27]
	v_mfma_f32_16x16x32_bf16 v[20:23], v[100:103], v[202:205], v[20:23]
	v_mfma_f32_16x16x32_bf16 v[20:23], v[104:107], v[210:213], v[20:23]
	v_mfma_f32_16x16x32_bf16 v[16:19], v[92:95], v[214:217], v[16:19]
	v_mfma_f32_16x16x32_bf16 v[16:19], v[96:99], v[218:221], v[16:19]
	v_mfma_f32_16x16x32_bf16 v[12:15], v[100:103], v[214:217], v[12:15]
	v_mfma_f32_16x16x32_bf16 v[12:15], v[104:107], v[218:221], v[12:15]
	s_barrier
	s_add_i32 s15, 0, 0x18000
	s_add_i32 s16, 0, 0x1c000
	v_add_u32_e32 v88, s15, v193
	v_add_u32_e32 v104, s16, v193
	ds_read_b128 v[72:75], v88
	ds_read_b128 v[76:79], v88 offset:1024
	ds_read_b128 v[84:87], v88 offset:2048
	ds_read_b128 v[88:91], v88 offset:3072
	ds_read_b128 v[92:95], v104
	ds_read_b128 v[96:99], v104 offset:1024
	ds_read_b128 v[100:103], v104 offset:2048
	ds_read_b128 v[104:107], v104 offset:3072
	s_add_u32 s78, s78, 0x80000
	s_addc_u32 s79, s79, 0
	s_mov_b32 m0, s88
	v_lshl_add_u64 v[224:225], s[78:79], 0, v[180:181]
	ds_read_b128 v[164:167], v200 offset:32768
	ds_read_b128 v[168:171], v200 offset:33792
	ds_read_b128 v[172:175], v200 offset:34816
	ds_read_b128 v[176:179], v200 offset:35840
	ds_read_b128 v[202:205], v200 offset:36864
	ds_read_b128 v[210:213], v200 offset:37888
	ds_read_b128 v[214:217], v200 offset:38912
	ds_read_b128 v[218:221], v200 offset:39936
	global_load_lds_dwordx4 v[224:225], off
	v_lshl_add_u64 v[224:225], s[78:79], 0, v[182:183]
	s_mov_b32 m0, s89
	s_nop 0
	global_load_lds_dwordx4 v[224:225], off
	s_waitcnt vmcnt(8)
	s_waitcnt lgkmcnt(0)
	s_barrier
	s_waitcnt lgkmcnt(0)
	v_mfma_f32_16x16x32_bf16 v[160:163], v[72:75], v[164:167], v[160:163]
	v_mfma_f32_16x16x32_bf16 v[160:163], v[76:79], v[168:171], v[160:163]
	v_mfma_f32_16x16x32_bf16 v[156:159], v[84:87], v[164:167], v[156:159]
	v_mfma_f32_16x16x32_bf16 v[156:159], v[88:91], v[168:171], v[156:159]
	v_mfma_f32_16x16x32_bf16 v[144:147], v[72:75], v[172:175], v[144:147]
	v_mfma_f32_16x16x32_bf16 v[144:147], v[76:79], v[176:179], v[144:147]
	v_mfma_f32_16x16x32_bf16 v[140:143], v[84:87], v[172:175], v[140:143]
	v_mfma_f32_16x16x32_bf16 v[140:143], v[88:91], v[176:179], v[140:143]
	v_mfma_f32_16x16x32_bf16 v[128:131], v[72:75], v[202:205], v[128:131]
	v_mfma_f32_16x16x32_bf16 v[128:131], v[76:79], v[210:213], v[128:131]
	v_mfma_f32_16x16x32_bf16 v[124:127], v[84:87], v[202:205], v[124:127]
	v_mfma_f32_16x16x32_bf16 v[124:127], v[88:91], v[210:213], v[124:127]
	v_mfma_f32_16x16x32_bf16 v[80:83], v[72:75], v[214:217], v[80:83]
	v_mfma_f32_16x16x32_bf16 v[80:83], v[76:79], v[218:221], v[80:83]
	v_mfma_f32_16x16x32_bf16 v[68:71], v[84:87], v[214:217], v[68:71]
	v_mfma_f32_16x16x32_bf16 v[68:71], v[88:91], v[218:221], v[68:71]
	v_mfma_f32_16x16x32_bf16 v[152:155], v[92:95], v[164:167], v[152:155]
	v_mfma_f32_16x16x32_bf16 v[152:155], v[96:99], v[168:171], v[152:155]
	v_mfma_f32_16x16x32_bf16 v[148:151], v[100:103], v[164:167], v[148:151]
	v_mfma_f32_16x16x32_bf16 v[148:151], v[104:107], v[168:171], v[148:151]
	v_mfma_f32_16x16x32_bf16 v[136:139], v[92:95], v[172:175], v[136:139]
	v_mfma_f32_16x16x32_bf16 v[136:139], v[96:99], v[176:179], v[136:139]
	v_mfma_f32_16x16x32_bf16 v[132:135], v[100:103], v[172:175], v[132:135]
	v_mfma_f32_16x16x32_bf16 v[132:135], v[104:107], v[176:179], v[132:135]
	v_mfma_f32_16x16x32_bf16 v[120:123], v[92:95], v[202:205], v[120:123]
	v_mfma_f32_16x16x32_bf16 v[120:123], v[96:99], v[210:213], v[120:123]
	v_mfma_f32_16x16x32_bf16 v[116:119], v[100:103], v[202:205], v[116:119]
	v_mfma_f32_16x16x32_bf16 v[116:119], v[104:107], v[210:213], v[116:119]
	v_mfma_f32_16x16x32_bf16 v[112:115], v[92:95], v[214:217], v[112:115]
	v_mfma_f32_16x16x32_bf16 v[112:115], v[96:99], v[218:221], v[112:115]
	v_mfma_f32_16x16x32_bf16 v[108:111], v[100:103], v[214:217], v[108:111]
	v_mfma_f32_16x16x32_bf16 v[108:111], v[104:107], v[218:221], v[108:111]
	s_barrier
; #define PG8_LAS __attribute__((address_space(3)))
; #define PG8_STAGE(bufoff, gbase, voff) do { _Pragma("unroll") for (int _i = 0; _i < 2; ++_i) \
;         __builtin_amdgcn_global_load_lds((const unsigned*)((const char*)(gbase) + (voff)[_i]), (PG8_LAS unsigned*)(lds + (bufoff) + ldsw + _i * 8192), 16, 0, 0); } while (0)
; #define PG8_LDA(dst, b, h) do { _Pragma("unroll") for (int m = 0; m < 4; ++m) _Pragma("unroll") for (int k = 0; k < 2; ++k) dst[m][k] = *(const PG8_LAS bf16x8*)(lds + PG8_SA(b, h) + aoff + m * 2048 + k * 1024); } while (0)
; #define PG8_MMA(ai, bj, At, Bt) do { __builtin_amdgcn_s_setprio(1); _Pragma("unroll") for (int m = 0; m < 4; ++m) _Pragma("unroll") for (int n = 0; n < 2; ++n) _Pragma("unroll") for (int k = 0; k < 2; ++k) \
;         acc[ai][bj][m][n] = __builtin_amdgcn_mfma_f32_16x16x32_bf16(Bt[n][k], At[m][k], acc[ai][bj][m][n], 0, 0, 0); __builtin_amdgcn_s_setprio(0); } while (0)
; #define PG8_WAIT_V(n) asm volatile("s_waitcnt vmcnt(" #n ")" ::: "memory")
; #define PG8_WAIT_L(n) asm volatile("s_waitcnt lgkmcnt(" #n ")" ::: "memory")
; #define PG8_BAR __builtin_amdgcn_s_barrier()
; #define PG8_SCHED __builtin_amdgcn_sched_barrier(0)
;     __device__ __forceinline__ void operator()(const f32x4 (&acc)[2][2][4][2], const Unit& u, int wr, int wc, int fr, int fq) const {
;     ...
;             if (fr == 0)  { *(PG8_LAS f32x4*)(xme + (ai * 2 + 0) * 32) = acc[ai][1][0][0]; *(PG8_LAS f32x4*)(xme + (ai * 2 + 0) * 32 + 4) = acc[ai][1][0][1]; }
; template <class Epi, class Sched, bool ALIGN_EPI = true>
; __device__ __forceinline__ void gemm_phase(PG8_LAS unsigned char* lds, const Gemm g, const Sched& S, const Epi& E, const int tid) {
;     ...
;             PG8_LDA(At, 1, 1); PG8_STAGE(PG8_SB(1, 0), b3, voffB); PG8_STAGE(PG8_SB(1, 1), b3 + hstepB, voffB); PG8_STAGE(PG8_SA(1, 0), a3, voffA);
;             PG8_WAIT_V(8); PG8_WAIT_L(0); PG8_BAR; PG8_MMA(1, 0, At, B0); PG8_MMA(1, 1, At, B1); PG8_BAR; PG8_SCHED;
;         }
;         if constexpr (ALIGN_EPI) { if (wr == 0) PG8_BAR; }
	s_add_i32 s15, s15, s85
	v_lshl_add_u64 v[190:191], v[190:191], 0, s[36:37]
	s_mov_b32 m0, s15
	ds_read_b128 v[164:167], v200 offset:49152
	ds_read_b128 v[168:171], v200 offset:50176
	ds_read_b128 v[172:175], v200 offset:51200
	ds_read_b128 v[176:179], v200 offset:52224
	ds_read_b128 v[202:205], v200 offset:53248
	ds_read_b128 v[210:213], v200 offset:54272
	ds_read_b128 v[214:217], v200 offset:55296
	ds_read_b128 v[218:221], v200 offset:56320
	global_load_lds_dwordx4 v[190:191], off
	s_add_i32 m0, s15, 0x2000
	s_add_u32 s76, s76, 0x80080
	v_lshl_add_u64 v[190:191], v[206:207], 0, s[36:37]
	s_addc_u32 s77, s77, 0
	s_add_i32 s15, s16, s85
	global_load_lds_dwordx4 v[190:191], off
	v_lshl_add_u64 v[190:191], s[76:77], 0, v[2:3]
	s_mov_b32 m0, s15
	s_nop 0
	global_load_lds_dwordx4 v[190:191], off
	v_lshl_add_u64 v[190:191], s[76:77], 0, v[184:185]
	s_add_i32 m0, s15, 0x2000
	s_nop 0
	global_load_lds_dwordx4 v[190:191], off
	v_lshl_add_u64 v[190:191], v[208:209], 0, s[36:37]
	s_mov_b32 m0, s92
	s_nop 0
	global_load_lds_dwordx4 v[190:191], off
	v_lshl_add_u64 v[190:191], v[222:223], 0, s[36:37]
	s_mov_b32 m0, s93
	s_nop 0
	global_load_lds_dwordx4 v[190:191], off
	s_waitcnt vmcnt(8)
	s_waitcnt lgkmcnt(0)
	s_barrier
	s_waitcnt lgkmcnt(0)
	v_mfma_f32_16x16x32_bf16 v[64:67], v[72:75], v[164:167], v[64:67]
	v_mfma_f32_16x16x32_bf16 v[64:67], v[76:79], v[168:171], v[64:67]
	v_mfma_f32_16x16x32_bf16 v[60:63], v[84:87], v[164:167], v[60:63]
	v_mfma_f32_16x16x32_bf16 v[60:63], v[88:91], v[168:171], v[60:63]
	v_mfma_f32_16x16x32_bf16 v[48:51], v[72:75], v[172:175], v[48:51]
	v_mfma_f32_16x16x32_bf16 v[48:51], v[76:79], v[176:179], v[48:51]
	v_mfma_f32_16x16x32_bf16 v[44:47], v[84:87], v[172:175], v[44:47]
	v_mfma_f32_16x16x32_bf16 v[44:47], v[88:91], v[176:179], v[44:47]
	v_mfma_f32_16x16x32_bf16 v[32:35], v[72:75], v[202:205], v[32:35]
	v_mfma_f32_16x16x32_bf16 v[32:35], v[76:79], v[210:213], v[32:35]
	v_mfma_f32_16x16x32_bf16 v[28:31], v[84:87], v[202:205], v[28:31]
	v_mfma_f32_16x16x32_bf16 v[28:31], v[88:91], v[210:213], v[28:31]
	v_mfma_f32_16x16x32_bf16 v[8:11], v[72:75], v[214:217], v[8:11]
	v_mfma_f32_16x16x32_bf16 v[8:11], v[76:79], v[218:221], v[8:11]
	v_mfma_f32_16x16x32_bf16 v[4:7], v[84:87], v[214:217], v[4:7]
	v_mfma_f32_16x16x32_bf16 v[4:7], v[88:91], v[218:221], v[4:7]
	v_mfma_f32_16x16x32_bf16 v[56:59], v[92:95], v[164:167], v[56:59]
	v_mfma_f32_16x16x32_bf16 v[56:59], v[96:99], v[168:171], v[56:59]
	v_mfma_f32_16x16x32_bf16 v[52:55], v[100:103], v[164:167], v[52:55]
	v_mfma_f32_16x16x32_bf16 v[52:55], v[104:107], v[168:171], v[52:55]
	v_mfma_f32_16x16x32_bf16 v[40:43], v[92:95], v[172:175], v[40:43]
	v_mfma_f32_16x16x32_bf16 v[40:43], v[96:99], v[176:179], v[40:43]
	v_mfma_f32_16x16x32_bf16 v[36:39], v[100:103], v[172:175], v[36:39]
	v_mfma_f32_16x16x32_bf16 v[36:39], v[104:107], v[176:179], v[36:39]
	v_mfma_f32_16x16x32_bf16 v[24:27], v[92:95], v[202:205], v[24:27]
	v_mfma_f32_16x16x32_bf16 v[24:27], v[96:99], v[210:213], v[24:27]
	v_mfma_f32_16x16x32_bf16 v[20:23], v[100:103], v[202:205], v[20:23]
	v_mfma_f32_16x16x32_bf16 v[20:23], v[104:107], v[210:213], v[20:23]
	v_mfma_f32_16x16x32_bf16 v[16:19], v[92:95], v[214:217], v[16:19]
	v_mfma_f32_16x16x32_bf16 v[16:19], v[96:99], v[218:221], v[16:19]
	v_mfma_f32_16x16x32_bf16 v[12:15], v[100:103], v[214:217], v[12:15]
	v_mfma_f32_16x16x32_bf16 v[12:15], v[104:107], v[218:221], v[12:15]
	s_barrier
	s_add_i32 s21, s21, 2
	s_add_u32 s74, s74, 0x100
	s_addc_u32 s75, s75, 0
	s_add_u32 s19, s19, 0x100
	s_addc_u32 s20, s20, 0
	s_cmp_gt_u32 s21, 29
	s_cbranch_scc0 .LBB0_1238
	s_and_b64 vcc, exec, s[56:57]
	s_cbranch_vccnz .LBB0_1264
	s_and_saveexec_b64 s[18:19], s[38:39]
	s_cbranch_execnz .LBB0_1265

; #define PG8_STAGE(bufoff, gbase, voff) do { _Pragma("unroll") for (int _i = 0; _i < 2; ++_i) \
;         __builtin_amdgcn_global_load_lds((const unsigned*)((const char*)(gbase) + (voff)[_i]), (PG8_LAS unsigned*)(lds + (bufoff) + ldsw + _i * 8192), 16, 0, 0); } while (0)
; #define PG8_LDA(dst, b, h) do { _Pragma("unroll") for (int m = 0; m < 4; ++m) _Pragma("unroll") for (int k = 0; k < 2; ++k) dst[m][k] = *(const PG8_LAS bf16x8*)(lds + PG8_SA(b, h) + aoff + m * 2048 + k * 1024); } while (0)
; #define PG8_LDB(dst, b, h) do { _Pragma("unroll") for (int n = 0; n < 2; ++n) _Pragma("unroll") for (int k = 0; k < 2; ++k) dst[n][k] = *(const PG8_LAS bf16x8*)(lds + PG8_SB(b, h) + boff + n * 2048 + k * 1024); } while (0)
; #define PG8_MMA(ai, bj, At, Bt) do { __builtin_amdgcn_s_setprio(1); _Pragma("unroll") for (int m = 0; m < 4; ++m) _Pragma("unroll") for (int n = 0; n < 2; ++n) _Pragma("unroll") for (int k = 0; k < 2; ++k) \
;         acc[ai][bj][m][n] = __builtin_amdgcn_mfma_f32_16x16x32_bf16(Bt[n][k], At[m][k], acc[ai][bj][m][n], 0, 0, 0); __builtin_amdgcn_s_setprio(0); } while (0)
; #define PG8_WAIT_V(n) asm volatile("s_waitcnt vmcnt(" #n ")" ::: "memory")
; #define PG8_WAIT_L(n) asm volatile("s_waitcnt lgkmcnt(" #n ")" ::: "memory")
; template <class Epi, class Sched, bool ALIGN_EPI = true>
; __device__ __forceinline__ void gemm_phase(PG8_LAS unsigned char* lds, const Gemm g, const Sched& S, const Epi& E, const int tid) {
;     ...
;         for (int t = 0; t < nt; t += 2) {
;             const bool last = (t == nt - 2);
;             const char* a1 = cA + (size_t)(t + 1) * kstep;
;             const char* a2 = last ? nA : cA + (size_t)(t + 2) * kstep; const char* b2 = last ? nB : cB + (size_t)(t + 2) * kstep;
;             const char* a3 = a2 + kstep; const char* b3 = b2 + kstep;
;             if (last && has_next) S.a_ready(nxt);
;             PG8_LDB(B0, 0, 0); PG8_LDB(B1, 0, 1); PG8_SCHED; PG8_LDA(At, 0, 0); PG8_STAGE(PG8_SA(1, 1), a1 + hstepA, voffA);
;             PG8_WAIT_V(8); PG8_WAIT_L(0); PG8_BAR; PG8_MMA(0, 0, At, B0); PG8_MMA(0, 1, At, B1); PG8_BAR; PG8_SCHED;
;             PG8_LDA(At, 0, 1); PG8_STAGE(PG8_SB(0, 0), b2, voffB); PG8_STAGE(PG8_SB(0, 1), b2 + hstepB, voffB); PG8_STAGE(PG8_SA(0, 0), a2, voffA);
;             PG8_WAIT_V(8); PG8_WAIT_L(0); PG8_BAR; PG8_MMA(1, 0, At, B0); PG8_MMA(1, 1, At, B1); PG8_BAR; PG8_SCHED;
.LBB0_1414:
	s_add_i32 s70, s12, 2
	s_add_u32 s10, s0, 0x100
	s_addc_u32 s11, s1, 0
	s_add_i32 s15, 0, 0x10000
	s_cmp_eq_u32 s45, s12
	s_cselect_b32 s23, s47, s11
	s_cselect_b32 s22, s46, s10
	s_cselect_b32 s13, s49, s69
	s_cselect_b32 s12, s48, s68
	s_add_i32 s16, 0, 0x14000
	v_add_u32_e32 v72, s15, v251
	v_add_u32_e32 v128, s16, v251
	ds_read_b128 v[56:59], v72
	ds_read_b128 v[60:63], v72 offset:1024
	ds_read_b128 v[68:71], v72 offset:2048
	ds_read_b128 v[72:75], v72 offset:3072
	ds_read_b128 v[92:95], v128
	ds_read_b128 v[104:107], v128 offset:1024
	ds_read_b128 v[116:119], v128 offset:2048
	ds_read_b128 v[128:131], v128 offset:3072
	v_lshl_add_u64 v[196:197], s[0:1], 0, v[216:217]
	s_add_i32 m0, s52, 0xc000
	ds_read_b128 v[140:143], v252
	ds_read_b128 v[152:155], v252 offset:1024
	ds_read_b128 v[156:159], v252 offset:2048
	ds_read_b128 v[160:163], v252 offset:3072
	ds_read_b128 v[172:175], v252 offset:4096
	ds_read_b128 v[184:187], v252 offset:5120
	ds_read_b128 v[188:191], v252 offset:6144
	ds_read_b128 v[192:195], v252 offset:7168
	global_load_lds_dwordx4 v[196:197], off
	v_lshl_add_u64 v[196:197], s[0:1], 0, v[218:219]
	s_add_i32 m0, s52, 0xe000
	s_nop 0
	global_load_lds_dwordx4 v[196:197], off
	s_waitcnt vmcnt(8)
	s_waitcnt lgkmcnt(0)
	s_barrier
	s_waitcnt lgkmcnt(0)
	v_mfma_f32_16x16x32_bf16 v[180:183], v[56:59], v[140:143], v[180:183]
	v_mfma_f32_16x16x32_bf16 v[180:183], v[60:63], v[152:155], v[180:183]
	v_mfma_f32_16x16x32_bf16 v[176:179], v[68:71], v[140:143], v[176:179]
	v_mfma_f32_16x16x32_bf16 v[176:179], v[72:75], v[152:155], v[176:179]
	v_mfma_f32_16x16x32_bf16 v[148:151], v[56:59], v[156:159], v[148:151]
	v_mfma_f32_16x16x32_bf16 v[148:151], v[60:63], v[160:163], v[148:151]
	v_mfma_f32_16x16x32_bf16 v[144:147], v[68:71], v[156:159], v[144:147]
	v_mfma_f32_16x16x32_bf16 v[144:147], v[72:75], v[160:163], v[144:147]
	v_mfma_f32_16x16x32_bf16 v[124:127], v[56:59], v[172:175], v[124:127]
	v_mfma_f32_16x16x32_bf16 v[124:127], v[60:63], v[184:187], v[124:127]
	v_mfma_f32_16x16x32_bf16 v[120:123], v[68:71], v[172:175], v[120:123]
	v_mfma_f32_16x16x32_bf16 v[120:123], v[72:75], v[184:187], v[120:123]
	v_mfma_f32_16x16x32_bf16 v[100:103], v[56:59], v[188:191], v[100:103]
	v_mfma_f32_16x16x32_bf16 v[100:103], v[60:63], v[192:195], v[100:103]
	v_mfma_f32_16x16x32_bf16 v[96:99], v[68:71], v[188:191], v[96:99]
	v_mfma_f32_16x16x32_bf16 v[96:99], v[72:75], v[192:195], v[96:99]
	v_mfma_f32_16x16x32_bf16 v[168:171], v[92:95], v[140:143], v[168:171]
	v_mfma_f32_16x16x32_bf16 v[136:139], v[92:95], v[156:159], v[136:139]
	v_mfma_f32_16x16x32_bf16 v[132:135], v[116:119], v[156:159], v[132:135]
	v_mfma_f32_16x16x32_bf16 v[112:115], v[92:95], v[172:175], v[112:115]
	v_mfma_f32_16x16x32_bf16 v[108:111], v[116:119], v[172:175], v[108:111]
	v_mfma_f32_16x16x32_bf16 v[88:91], v[92:95], v[188:191], v[88:91]
	v_mfma_f32_16x16x32_bf16 v[84:87], v[116:119], v[188:191], v[84:87]
	v_mfma_f32_16x16x32_bf16 v[168:171], v[104:107], v[152:155], v[168:171]
	v_mfma_f32_16x16x32_bf16 v[140:143], v[116:119], v[140:143], v[164:167]
	v_mfma_f32_16x16x32_bf16 v[136:139], v[104:107], v[160:163], v[136:139]
	v_mfma_f32_16x16x32_bf16 v[132:135], v[128:131], v[160:163], v[132:135]
	v_mfma_f32_16x16x32_bf16 v[112:115], v[104:107], v[184:187], v[112:115]
	v_mfma_f32_16x16x32_bf16 v[108:111], v[128:131], v[184:187], v[108:111]
	v_mfma_f32_16x16x32_bf16 v[88:91], v[104:107], v[192:195], v[88:91]
	v_mfma_f32_16x16x32_bf16 v[84:87], v[128:131], v[192:195], v[84:87]
	v_mfma_f32_16x16x32_bf16 v[140:143], v[128:131], v[152:155], v[140:143]
	s_barrier
	s_add_i32 s0, s15, s51
	v_lshl_add_u64 v[200:201], s[12:13], 0, v[2:3]
	s_mov_b32 m0, s0
	ds_read_b128 v[152:155], v252 offset:16384
	ds_read_b128 v[156:159], v252 offset:17408
	ds_read_b128 v[160:163], v252 offset:18432
	ds_read_b128 v[164:167], v252 offset:19456
	ds_read_b128 v[172:175], v252 offset:20480
	ds_read_b128 v[184:187], v252 offset:21504
	ds_read_b128 v[188:191], v252 offset:22528
	ds_read_b128 v[192:195], v252 offset:23552
	global_load_lds_dwordx4 v[200:201], off
	s_add_i32 m0, s0, 0x2000
	s_add_u32 s0, s12, 0x168000
	v_lshl_add_u64 v[202:203], s[12:13], 0, v[214:215]
	s_addc_u32 s1, s13, 0
	s_add_i32 s15, s16, s51
	global_load_lds_dwordx4 v[202:203], off
	v_lshl_add_u64 v[196:197], s[0:1], 0, v[2:3]
	s_mov_b32 m0, s15
	v_lshl_add_u64 v[204:205], s[22:23], 0, v[210:211]
	global_load_lds_dwordx4 v[196:197], off
	v_lshl_add_u64 v[196:197], s[0:1], 0, v[214:215]
	s_add_i32 m0, s15, 0x2000
	v_lshl_add_u64 v[206:207], s[22:23], 0, v[212:213]
	global_load_lds_dwordx4 v[196:197], off
	s_mov_b32 m0, s52
	s_nop 0
	global_load_lds_dwordx4 v[204:205], off
	s_mov_b32 m0, s53
	s_nop 0
	global_load_lds_dwordx4 v[206:207], off
	s_waitcnt vmcnt(8)
	s_waitcnt lgkmcnt(0)
	s_barrier
; #define PG8_STAGE(bufoff, gbase, voff) do { _Pragma("unroll") for (int _i = 0; _i < 2; ++_i) \
;         __builtin_amdgcn_global_load_lds((const unsigned*)((const char*)(gbase) + (voff)[_i]), (PG8_LAS unsigned*)(lds + (bufoff) + ldsw + _i * 8192), 16, 0, 0); } while (0)
; #define PG8_LDA(dst, b, h) do { _Pragma("unroll") for (int m = 0; m < 4; ++m) _Pragma("unroll") for (int k = 0; k < 2; ++k) dst[m][k] = *(const PG8_LAS bf16x8*)(lds + PG8_SA(b, h) + aoff + m * 2048 + k * 1024); } while (0)
; #define PG8_LDB(dst, b, h) do { _Pragma("unroll") for (int n = 0; n < 2; ++n) _Pragma("unroll") for (int k = 0; k < 2; ++k) dst[n][k] = *(const PG8_LAS bf16x8*)(lds + PG8_SB(b, h) + boff + n * 2048 + k * 1024); } while (0)
; #define PG8_MMA(ai, bj, At, Bt) do { __builtin_amdgcn_s_setprio(1); _Pragma("unroll") for (int m = 0; m < 4; ++m) _Pragma("unroll") for (int n = 0; n < 2; ++n) _Pragma("unroll") for (int k = 0; k < 2; ++k) \
;         acc[ai][bj][m][n] = __builtin_amdgcn_mfma_f32_16x16x32_bf16(Bt[n][k], At[m][k], acc[ai][bj][m][n], 0, 0, 0); __builtin_amdgcn_s_setprio(0); } while (0)
; #define PG8_WAIT_V(n) asm volatile("s_waitcnt vmcnt(" #n ")" ::: "memory")
; #define PG8_WAIT_L(n) asm volatile("s_waitcnt lgkmcnt(" #n ")" ::: "memory")
; #define PG8_BAR __builtin_amdgcn_s_barrier()
; #define PG8_SCHED __builtin_amdgcn_sched_barrier(0)
; template <class Epi, class Sched, bool ALIGN_EPI = true>
; __device__ __forceinline__ void gemm_phase(PG8_LAS unsigned char* lds, const Gemm g, const Sched& S, const Epi& E, const int tid) {
;     ...
;             PG8_WAIT_V(8); PG8_WAIT_L(0); PG8_BAR; PG8_MMA(1, 0, At, B0); PG8_MMA(1, 1, At, B1); PG8_BAR; PG8_SCHED;
;             PG8_LDB(B0, 1, 0); PG8_LDB(B1, 1, 1); PG8_SCHED; PG8_LDA(At, 1, 0); PG8_STAGE(PG8_SA(0, 1), a2 + hstepA, voffA);
;             PG8_WAIT_V(8); PG8_WAIT_L(0); PG8_BAR; PG8_MMA(0, 0, At, B0); PG8_MMA(0, 1, At, B1); PG8_BAR; PG8_SCHED;
	s_waitcnt lgkmcnt(0)
	v_mfma_f32_16x16x32_bf16 v[80:83], v[56:59], v[152:155], v[80:83]
	v_mfma_f32_16x16x32_bf16 v[80:83], v[60:63], v[156:159], v[80:83]
	v_mfma_f32_16x16x32_bf16 v[76:79], v[68:71], v[152:155], v[76:79]
	v_mfma_f32_16x16x32_bf16 v[76:79], v[72:75], v[156:159], v[76:79]
	v_mfma_f32_16x16x32_bf16 v[48:51], v[56:59], v[160:163], v[48:51]
	v_mfma_f32_16x16x32_bf16 v[48:51], v[60:63], v[164:167], v[48:51]
	v_mfma_f32_16x16x32_bf16 v[44:47], v[68:71], v[160:163], v[44:47]
	v_mfma_f32_16x16x32_bf16 v[44:47], v[72:75], v[164:167], v[44:47]
	v_mfma_f32_16x16x32_bf16 v[32:35], v[56:59], v[172:175], v[32:35]
	v_mfma_f32_16x16x32_bf16 v[32:35], v[60:63], v[184:187], v[32:35]
	v_mfma_f32_16x16x32_bf16 v[28:31], v[68:71], v[172:175], v[28:31]
	v_mfma_f32_16x16x32_bf16 v[28:31], v[72:75], v[184:187], v[28:31]
	v_mfma_f32_16x16x32_bf16 v[16:19], v[56:59], v[188:191], v[16:19]
	v_mfma_f32_16x16x32_bf16 v[16:19], v[60:63], v[192:195], v[16:19]
	v_mfma_f32_16x16x32_bf16 v[12:15], v[68:71], v[188:191], v[12:15]
	v_mfma_f32_16x16x32_bf16 v[12:15], v[72:75], v[192:195], v[12:15]
	v_mfma_f32_16x16x32_bf16 v[52:55], v[116:119], v[152:155], v[52:55]
	v_mfma_f32_16x16x32_bf16 v[40:43], v[92:95], v[160:163], v[40:43]
	v_mfma_f32_16x16x32_bf16 v[36:39], v[116:119], v[160:163], v[36:39]
	v_mfma_f32_16x16x32_bf16 v[24:27], v[92:95], v[172:175], v[24:27]
	v_mfma_f32_16x16x32_bf16 v[20:23], v[116:119], v[172:175], v[20:23]
	v_mfma_f32_16x16x32_bf16 v[8:11], v[92:95], v[188:191], v[8:11]
	v_mfma_f32_16x16x32_bf16 v[4:7], v[116:119], v[188:191], v[4:7]
	v_mfma_f32_16x16x32_bf16 v[56:59], v[92:95], v[152:155], v[64:67]
	v_mfma_f32_16x16x32_bf16 v[52:55], v[128:131], v[156:159], v[52:55]
	v_mfma_f32_16x16x32_bf16 v[40:43], v[104:107], v[164:167], v[40:43]
	v_mfma_f32_16x16x32_bf16 v[36:39], v[128:131], v[164:167], v[36:39]
	v_mfma_f32_16x16x32_bf16 v[24:27], v[104:107], v[184:187], v[24:27]
	v_mfma_f32_16x16x32_bf16 v[20:23], v[128:131], v[184:187], v[20:23]
	v_mfma_f32_16x16x32_bf16 v[8:11], v[104:107], v[192:195], v[8:11]
	v_mfma_f32_16x16x32_bf16 v[4:7], v[128:131], v[192:195], v[4:7]
	v_mfma_f32_16x16x32_bf16 v[56:59], v[104:107], v[156:159], v[56:59]
	s_barrier
	s_add_i32 s15, 0, 0x18000
	s_add_i32 s16, 0, 0x1c000
	v_add_u32_e32 v72, s15, v251
	v_add_u32_e32 v128, s16, v251
	ds_read_b128 v[60:63], v72
	ds_read_b128 v[64:67], v72 offset:1024
	ds_read_b128 v[68:71], v72 offset:2048
	ds_read_b128 v[72:75], v72 offset:3072
	ds_read_b128 v[92:95], v128
	ds_read_b128 v[104:107], v128 offset:1024
	ds_read_b128 v[116:119], v128 offset:2048
	ds_read_b128 v[128:131], v128 offset:3072
	s_add_u32 s0, s22, 0x168000
	s_addc_u32 s1, s23, 0
	s_mov_b32 m0, s54
	v_lshl_add_u64 v[164:165], s[0:1], 0, v[210:211]
	ds_read_b128 v[152:155], v252 offset:32768
	ds_read_b128 v[156:159], v252 offset:33792
	ds_read_b128 v[160:163], v252 offset:34816
	ds_read_b128 v[172:175], v252 offset:35840
	ds_read_b128 v[184:187], v252 offset:36864
	ds_read_b128 v[188:191], v252 offset:37888
	ds_read_b128 v[192:195], v252 offset:38912
	ds_read_b128 v[196:199], v252 offset:39936
	global_load_lds_dwordx4 v[164:165], off
	v_lshl_add_u64 v[164:165], s[0:1], 0, v[212:213]
	s_mov_b32 m0, s55
	s_nop 0
	global_load_lds_dwordx4 v[164:165], off
	s_waitcnt vmcnt(8)
	s_waitcnt lgkmcnt(0)
	s_barrier
	s_waitcnt lgkmcnt(0)
	v_mfma_f32_16x16x32_bf16 v[164:167], v[60:63], v[152:155], v[180:183]
	v_mfma_f32_16x16x32_bf16 v[180:183], v[64:67], v[156:159], v[164:167]
	v_mfma_f32_16x16x32_bf16 v[164:167], v[68:71], v[152:155], v[176:179]
	v_mfma_f32_16x16x32_bf16 v[148:151], v[60:63], v[160:163], v[148:151]
	v_mfma_f32_16x16x32_bf16 v[144:147], v[68:71], v[160:163], v[144:147]
	v_mfma_f32_16x16x32_bf16 v[124:127], v[60:63], v[184:187], v[124:127]
	v_mfma_f32_16x16x32_bf16 v[120:123], v[68:71], v[184:187], v[120:123]
	v_mfma_f32_16x16x32_bf16 v[100:103], v[60:63], v[192:195], v[100:103]
	v_mfma_f32_16x16x32_bf16 v[96:99], v[68:71], v[192:195], v[96:99]
	v_mfma_f32_16x16x32_bf16 v[176:179], v[72:75], v[156:159], v[164:167]
	v_mfma_f32_16x16x32_bf16 v[148:151], v[64:67], v[172:175], v[148:151]
	v_mfma_f32_16x16x32_bf16 v[144:147], v[72:75], v[172:175], v[144:147]
	v_mfma_f32_16x16x32_bf16 v[124:127], v[64:67], v[188:191], v[124:127]
	v_mfma_f32_16x16x32_bf16 v[120:123], v[72:75], v[188:191], v[120:123]
	v_mfma_f32_16x16x32_bf16 v[100:103], v[64:67], v[196:199], v[100:103]
	v_mfma_f32_16x16x32_bf16 v[96:99], v[72:75], v[196:199], v[96:99]
	v_mfma_f32_16x16x32_bf16 v[164:167], v[92:95], v[152:155], v[168:171]
	v_mfma_f32_16x16x32_bf16 v[140:143], v[116:119], v[152:155], v[140:143]
	v_mfma_f32_16x16x32_bf16 v[136:139], v[92:95], v[160:163], v[136:139]
	v_mfma_f32_16x16x32_bf16 v[132:135], v[116:119], v[160:163], v[132:135]
	v_mfma_f32_16x16x32_bf16 v[112:115], v[92:95], v[184:187], v[112:115]
	v_mfma_f32_16x16x32_bf16 v[108:111], v[116:119], v[184:187], v[108:111]
	v_mfma_f32_16x16x32_bf16 v[88:91], v[92:95], v[192:195], v[88:91]
	v_mfma_f32_16x16x32_bf16 v[84:87], v[116:119], v[192:195], v[84:87]
	v_mfma_f32_16x16x32_bf16 v[168:171], v[104:107], v[156:159], v[164:167]
	v_mfma_f32_16x16x32_bf16 v[164:167], v[128:131], v[156:159], v[140:143]
	v_mfma_f32_16x16x32_bf16 v[136:139], v[104:107], v[172:175], v[136:139]
	v_mfma_f32_16x16x32_bf16 v[132:135], v[128:131], v[172:175], v[132:135]
	v_mfma_f32_16x16x32_bf16 v[112:115], v[104:107], v[188:191], v[112:115]
	v_mfma_f32_16x16x32_bf16 v[108:111], v[128:131], v[188:191], v[108:111]
	v_mfma_f32_16x16x32_bf16 v[88:91], v[104:107], v[196:199], v[88:91]
	v_mfma_f32_16x16x32_bf16 v[84:87], v[128:131], v[196:199], v[84:87]
	s_barrier
; #define PG8_STAGE(bufoff, gbase, voff) do { _Pragma("unroll") for (int _i = 0; _i < 2; ++_i) \
;         __builtin_amdgcn_global_load_lds((const unsigned*)((const char*)(gbase) + (voff)[_i]), (PG8_LAS unsigned*)(lds + (bufoff) + ldsw + _i * 8192), 16, 0, 0); } while (0)
; #define PG8_LDA(dst, b, h) do { _Pragma("unroll") for (int m = 0; m < 4; ++m) _Pragma("unroll") for (int k = 0; k < 2; ++k) dst[m][k] = *(const PG8_LAS bf16x8*)(lds + PG8_SA(b, h) + aoff + m * 2048 + k * 1024); } while (0)
; #define PG8_MMA(ai, bj, At, Bt) do { __builtin_amdgcn_s_setprio(1); _Pragma("unroll") for (int m = 0; m < 4; ++m) _Pragma("unroll") for (int n = 0; n < 2; ++n) _Pragma("unroll") for (int k = 0; k < 2; ++k) \
;         acc[ai][bj][m][n] = __builtin_amdgcn_mfma_f32_16x16x32_bf16(Bt[n][k], At[m][k], acc[ai][bj][m][n], 0, 0, 0); __builtin_amdgcn_s_setprio(0); } while (0)
; #define PG8_WAIT_V(n) asm volatile("s_waitcnt vmcnt(" #n ")" ::: "memory")
; #define PG8_WAIT_L(n) asm volatile("s_waitcnt lgkmcnt(" #n ")" ::: "memory")
; #define PG8_BAR __builtin_amdgcn_s_barrier()
; #define PG8_SCHED __builtin_amdgcn_sched_barrier(0)
; template <class Epi, class Sched, bool ALIGN_EPI = true>
; __device__ __forceinline__ void gemm_phase(PG8_LAS unsigned char* lds, const Gemm g, const Sched& S, const Epi& E, const int tid) {
;     ...
;             PG8_LDA(At, 1, 1); PG8_STAGE(PG8_SB(1, 0), b3, voffB); PG8_STAGE(PG8_SB(1, 1), b3 + hstepB, voffB); PG8_STAGE(PG8_SA(1, 0), a3, voffA);
;             PG8_WAIT_V(8); PG8_WAIT_L(0); PG8_BAR; PG8_MMA(1, 0, At, B0); PG8_MMA(1, 1, At, B1); PG8_BAR; PG8_SCHED;
;         }
;         if constexpr (ALIGN_EPI) { if (wr == 0) PG8_BAR; }
	s_add_i32 s0, s15, s51
	v_lshl_add_u64 v[196:197], v[200:201], 0, s[36:37]
	s_mov_b32 m0, s0
	ds_read_b128 v[140:143], v252 offset:49152
	ds_read_b128 v[152:155], v252 offset:50176
	ds_read_b128 v[156:159], v252 offset:51200
	ds_read_b128 v[160:163], v252 offset:52224
	ds_read_b128 v[172:175], v252 offset:53248
	ds_read_b128 v[184:187], v252 offset:54272
	ds_read_b128 v[188:191], v252 offset:55296
	ds_read_b128 v[192:195], v252 offset:56320
	global_load_lds_dwordx4 v[196:197], off
	s_add_i32 m0, s0, 0x2000
	s_add_u32 s0, s12, 0x168080
	v_lshl_add_u64 v[196:197], v[202:203], 0, s[36:37]
	s_addc_u32 s1, s13, 0
	s_add_i32 s12, s16, s51
	global_load_lds_dwordx4 v[196:197], off
	v_lshl_add_u64 v[196:197], s[0:1], 0, v[2:3]
	s_mov_b32 m0, s12
	s_nop 0
	global_load_lds_dwordx4 v[196:197], off
	v_lshl_add_u64 v[196:197], s[0:1], 0, v[214:215]
	s_add_i32 m0, s12, 0x2000
	s_nop 0
	global_load_lds_dwordx4 v[196:197], off
	v_lshl_add_u64 v[196:197], v[204:205], 0, s[36:37]
	s_mov_b32 m0, s58
	s_nop 0
	global_load_lds_dwordx4 v[196:197], off
	v_lshl_add_u64 v[196:197], v[206:207], 0, s[36:37]
	s_mov_b32 m0, s59
	s_nop 0
	global_load_lds_dwordx4 v[196:197], off
	s_waitcnt vmcnt(8)
	s_waitcnt lgkmcnt(0)
	s_barrier
	s_waitcnt lgkmcnt(0)
	v_mfma_f32_16x16x32_bf16 v[80:83], v[60:63], v[140:143], v[80:83]
	v_mfma_f32_16x16x32_bf16 v[80:83], v[64:67], v[152:155], v[80:83]
	v_mfma_f32_16x16x32_bf16 v[76:79], v[68:71], v[140:143], v[76:79]
	v_mfma_f32_16x16x32_bf16 v[76:79], v[72:75], v[152:155], v[76:79]
	v_mfma_f32_16x16x32_bf16 v[48:51], v[60:63], v[156:159], v[48:51]
	v_mfma_f32_16x16x32_bf16 v[48:51], v[64:67], v[160:163], v[48:51]
	v_mfma_f32_16x16x32_bf16 v[44:47], v[68:71], v[156:159], v[44:47]
	v_mfma_f32_16x16x32_bf16 v[44:47], v[72:75], v[160:163], v[44:47]
	v_mfma_f32_16x16x32_bf16 v[32:35], v[60:63], v[172:175], v[32:35]
	v_mfma_f32_16x16x32_bf16 v[32:35], v[64:67], v[184:187], v[32:35]
	v_mfma_f32_16x16x32_bf16 v[28:31], v[68:71], v[172:175], v[28:31]
	v_mfma_f32_16x16x32_bf16 v[28:31], v[72:75], v[184:187], v[28:31]
	v_mfma_f32_16x16x32_bf16 v[16:19], v[60:63], v[188:191], v[16:19]
	v_mfma_f32_16x16x32_bf16 v[16:19], v[64:67], v[192:195], v[16:19]
	v_mfma_f32_16x16x32_bf16 v[12:15], v[68:71], v[188:191], v[12:15]
	v_mfma_f32_16x16x32_bf16 v[12:15], v[72:75], v[192:195], v[12:15]
	v_mfma_f32_16x16x32_bf16 v[56:59], v[92:95], v[140:143], v[56:59]
	v_mfma_f32_16x16x32_bf16 v[52:55], v[116:119], v[140:143], v[52:55]
	v_mfma_f32_16x16x32_bf16 v[40:43], v[92:95], v[156:159], v[40:43]
	v_mfma_f32_16x16x32_bf16 v[36:39], v[116:119], v[156:159], v[36:39]
	v_mfma_f32_16x16x32_bf16 v[24:27], v[92:95], v[172:175], v[24:27]
	v_mfma_f32_16x16x32_bf16 v[20:23], v[116:119], v[172:175], v[20:23]
	v_mfma_f32_16x16x32_bf16 v[8:11], v[92:95], v[188:191], v[8:11]
	v_mfma_f32_16x16x32_bf16 v[4:7], v[116:119], v[188:191], v[4:7]
	v_mfma_f32_16x16x32_bf16 v[64:67], v[104:107], v[152:155], v[56:59]
	v_mfma_f32_16x16x32_bf16 v[52:55], v[128:131], v[152:155], v[52:55]
	v_mfma_f32_16x16x32_bf16 v[40:43], v[104:107], v[160:163], v[40:43]
	v_mfma_f32_16x16x32_bf16 v[36:39], v[128:131], v[160:163], v[36:39]
	v_mfma_f32_16x16x32_bf16 v[24:27], v[104:107], v[184:187], v[24:27]
	v_mfma_f32_16x16x32_bf16 v[20:23], v[128:131], v[184:187], v[20:23]
	v_mfma_f32_16x16x32_bf16 v[8:11], v[104:107], v[192:195], v[8:11]
	v_mfma_f32_16x16x32_bf16 v[4:7], v[128:131], v[192:195], v[4:7]
	s_barrier
	s_add_u32 s68, s68, 0x100
	s_addc_u32 s69, s69, 0
	s_cmp_ge_i32 s70, s67
	s_mov_b64 s[0:1], s[10:11]
	s_mov_b32 s12, s70
	s_cbranch_scc0 .LBB0_1414
	s_and_b64 vcc, exec, s[42:43]
	s_cbranch_vccz .LBB0_1417
	s_barrier
